# chained MFMA order; priority inverted: load segment (ds_read + LDS-DMA issue) at prio 1, MFMA segment at prio 0
# baseline (speedup 1.0000x reference)
; #define PG8_STAGE(bufoff, gbase, voff) do { const char* gb_ = (const char*)(gbase); asm volatile("" : "+s"(gb_)); _Pragma("unroll") for (int _i = 0; _i < 2; ++_i) { unsigned vo_ = (voff)[_i]; asm volatile("" : "+v"(vo_));        \
;         __builtin_amdgcn_global_load_lds((const unsigned*)(gb_ + vo_), (PG8_LAS unsigned*)(lds + (bufoff) + ldsw + _i * 8192), 16, 0, 0); } } while (0)
; #define PG8_LDA(dst, b, h) do { _Pragma("unroll") for (int m = 0; m < 4; ++m) _Pragma("unroll") for (int k = 0; k < 2; ++k) dst[m][k] = *(const PG8_LAS bf16x8*)(lds + PG8_SA(b, h) + aoff + m * 2048 + k * 1024); } while (0)
; #define PG8_LDB(dst, b, h) do { _Pragma("unroll") for (int n = 0; n < 2; ++n) _Pragma("unroll") for (int k = 0; k < 2; ++k) dst[n][k] = *(const PG8_LAS bf16x8*)(lds + PG8_SB(b, h) + boff + n * 2048 + k * 1024); } while (0)
; #define PG8_MMA(ai, bj, At, Bt) do { __builtin_amdgcn_s_setprio(1); _Pragma("unroll") for (int m = 0; m < 4; ++m) _Pragma("unroll") for (int n = 0; n < 2; ++n) _Pragma("unroll") for (int k = 0; k < 2; ++k) \
;         acc[ai][bj][m][n] = __builtin_amdgcn_mfma_f32_16x16x32_bf16(Bt[n][k], At[m][k], acc[ai][bj][m][n], 0, 0, 0); __builtin_amdgcn_s_setprio(0); } while (0)
; #define PG8_WAIT_V(n) asm volatile("s_waitcnt vmcnt(" #n ")" ::: "memory")
; #define PG8_WAIT_L(n) asm volatile("s_waitcnt lgkmcnt(" #n ")" ::: "memory")
; #define PG8_BAR __builtin_amdgcn_s_barrier()
; #define PG8_SCHED __builtin_amdgcn_sched_barrier(0)
; template <class Epi, class Sched, bool ALIGN_EPI = false, bool SP2 = false>
; __device__ __forceinline__ void gemm_phase(PG8_LAS unsigned char* lds, const Gemm g, const Sched& S, const Epi& E) {
;     ...
;             PG8_LDB(B0, 0, 0); PG8_LDB(B1, 0, 1); PG8_SCHED; PG8_LDA(At, 0, 0); PG8_STAGE(PG8_SA(1, 1), a1 + hstep, voffA);
;             PG8_WAIT_V(8); PG8_WAIT_L(0); PG8_BAR; PG8_MMA(0, 0, At, B0); PG8_MMA(0, 1, At, B1); PG8_BAR; PG8_SCHED;
;             PG8_LDA(At, 0, 1); PG8_STAGE(PG8_SB(0, 0), b2, voffB); PG8_STAGE(PG8_SB(0, 1), b2 + hstep, voffB); PG8_STAGE(PG8_SA(0, 0), a2, voffA);
;             PG8_WAIT_V(8); PG8_WAIT_L(0); PG8_BAR; PG8_MMA(1, 0, At, B0); PG8_MMA(1, 1, At, B1); PG8_BAR; PG8_SCHED;
.LBB0_232:
	s_add_u32 s2, s0, 0x100
	s_addc_u32 s3, s1, 0
	s_cmp_eq_u32 s30, 28
	s_cselect_b32 s10, s25, s2
	s_cselect_b32 s11, s24, s3
	s_cselect_b32 s8, s27, s28
	s_cselect_b32 s9, s26, s29
	s_add_u32 s6, s10, 0x80
	s_addc_u32 s7, s11, 0
	s_add_i32 s31, 0, 0x10000
	s_add_i32 s33, 0, 0x14000
	ds_read_b128 v[66:69], v244
	ds_read_b128 v[70:73], v244 offset:1024
	ds_read_b128 v[74:77], v244 offset:2048
	ds_read_b128 v[78:81], v244 offset:3072
	ds_read_b128 v[146:149], v244 offset:16384
	ds_read_b128 v[150:153], v244 offset:17408
	ds_read_b128 v[154:157], v244 offset:18432
	ds_read_b128 v[158:161], v244 offset:19456
	s_add_u32 s0, s0, 0x80080
	s_addc_u32 s1, s1, 0
	ds_read_b128 v[178:181], v223
	ds_read_b128 v[182:185], v223 offset:1024
	ds_read_b128 v[192:195], v223 offset:2048
	ds_read_b128 v[196:199], v223 offset:3072
	ds_read_b128 v[200:203], v223 offset:4096
	ds_read_b128 v[204:207], v223 offset:5120
	ds_read_b128 v[208:211], v223 offset:6144
	ds_read_b128 v[212:215], v223 offset:7168
	s_add_i32 m0, s13, 0xc000
	s_nop 0
	global_load_lds_dwordx4 v1, s[0:1]
	s_add_i32 m0, s13, 0xe000
	s_nop 0
	global_load_lds_dwordx4 v191, s[0:1]
	s_waitcnt vmcnt(8)
	s_waitcnt lgkmcnt(0)
	s_barrier
	s_setprio 0
	s_waitcnt lgkmcnt(0)
	v_mfma_f32_16x16x32_bf16 v[142:145], v[66:69], v[178:181], v[142:145]
	v_mfma_f32_16x16x32_bf16 v[142:145], v[70:73], v[182:185], v[142:145]
	v_mfma_f32_16x16x32_bf16 v[134:137], v[66:69], v[192:195], v[134:137]
	v_mfma_f32_16x16x32_bf16 v[134:137], v[70:73], v[196:199], v[134:137]
	v_mfma_f32_16x16x32_bf16 v[126:129], v[66:69], v[200:203], v[126:129]
	v_mfma_f32_16x16x32_bf16 v[126:129], v[70:73], v[204:207], v[126:129]
	v_mfma_f32_16x16x32_bf16 v[118:121], v[66:69], v[208:211], v[118:121]
	v_mfma_f32_16x16x32_bf16 v[118:121], v[70:73], v[212:215], v[118:121]
	v_mfma_f32_16x16x32_bf16 v[138:141], v[74:77], v[178:181], v[138:141]
	v_mfma_f32_16x16x32_bf16 v[138:141], v[78:81], v[182:185], v[138:141]
	v_mfma_f32_16x16x32_bf16 v[130:133], v[74:77], v[192:195], v[130:133]
	v_mfma_f32_16x16x32_bf16 v[130:133], v[78:81], v[196:199], v[130:133]
	v_mfma_f32_16x16x32_bf16 v[122:125], v[74:77], v[200:203], v[122:125]
	v_mfma_f32_16x16x32_bf16 v[122:125], v[78:81], v[204:207], v[122:125]
	v_mfma_f32_16x16x32_bf16 v[114:117], v[74:77], v[208:211], v[114:117]
	v_mfma_f32_16x16x32_bf16 v[114:117], v[78:81], v[212:215], v[114:117]
	v_mfma_f32_16x16x32_bf16 v[62:65], v[146:149], v[178:181], v[62:65]
	v_mfma_f32_16x16x32_bf16 v[62:65], v[150:153], v[182:185], v[62:65]
	v_mfma_f32_16x16x32_bf16 v[54:57], v[146:149], v[192:195], v[54:57]
	v_mfma_f32_16x16x32_bf16 v[54:57], v[150:153], v[196:199], v[54:57]
	v_mfma_f32_16x16x32_bf16 v[46:49], v[146:149], v[200:203], v[46:49]
	v_mfma_f32_16x16x32_bf16 v[46:49], v[150:153], v[204:207], v[46:49]
	v_mfma_f32_16x16x32_bf16 v[38:41], v[146:149], v[208:211], v[38:41]
	v_mfma_f32_16x16x32_bf16 v[38:41], v[150:153], v[212:215], v[38:41]
	v_mfma_f32_16x16x32_bf16 v[58:61], v[154:157], v[178:181], v[58:61]
	v_mfma_f32_16x16x32_bf16 v[58:61], v[158:161], v[182:185], v[58:61]
	v_mfma_f32_16x16x32_bf16 v[50:53], v[154:157], v[192:195], v[50:53]
	v_mfma_f32_16x16x32_bf16 v[50:53], v[158:161], v[196:199], v[50:53]
	v_mfma_f32_16x16x32_bf16 v[42:45], v[154:157], v[200:203], v[42:45]
	v_mfma_f32_16x16x32_bf16 v[42:45], v[158:161], v[204:207], v[42:45]
	v_mfma_f32_16x16x32_bf16 v[34:37], v[154:157], v[208:211], v[34:37]
	v_mfma_f32_16x16x32_bf16 v[34:37], v[158:161], v[212:215], v[34:37]
	s_setprio 1
	s_barrier
	s_mov_b64 s[0:1], s[8:9]
	s_add_i32 s31, s31, s12
	ds_read_b128 v[178:181], v223 offset:16384
	ds_read_b128 v[182:185], v223 offset:17408
	ds_read_b128 v[192:195], v223 offset:18432
	ds_read_b128 v[196:199], v223 offset:19456
	ds_read_b128 v[200:203], v223 offset:20480
	ds_read_b128 v[204:207], v223 offset:21504
	ds_read_b128 v[208:211], v223 offset:22528
	ds_read_b128 v[212:215], v223 offset:23552
	s_mov_b32 m0, s31
	s_nop 0
	global_load_lds_dwordx4 v189, s[0:1]
	s_add_i32 m0, s31, 0x2000
	s_nop 0
	global_load_lds_dwordx4 v219, s[0:1]
	s_add_u32 s0, s8, 0x80000
	s_addc_u32 s1, s9, 0
	s_add_i32 s31, s33, s12
	s_mov_b32 m0, s31
	s_nop 0
	global_load_lds_dwordx4 v189, s[0:1]
	s_add_i32 m0, s31, 0x2000
	s_nop 0
	global_load_lds_dwordx4 v219, s[0:1]
	s_mov_b64 s[0:1], s[10:11]
	s_mov_b32 m0, s13
	s_nop 0
	global_load_lds_dwordx4 v1, s[0:1]
	s_mov_b32 m0, s14
	s_nop 0
	global_load_lds_dwordx4 v191, s[0:1]
	s_waitcnt vmcnt(8)
	s_waitcnt lgkmcnt(0)
	s_barrier
	s_setprio 0
	s_waitcnt lgkmcnt(0)
	v_mfma_f32_16x16x32_bf16 v[110:113], v[66:69], v[178:181], v[110:113]
	v_mfma_f32_16x16x32_bf16 v[110:113], v[70:73], v[182:185], v[110:113]
	v_mfma_f32_16x16x32_bf16 v[102:105], v[66:69], v[192:195], v[102:105]
	v_mfma_f32_16x16x32_bf16 v[102:105], v[70:73], v[196:199], v[102:105]
	v_mfma_f32_16x16x32_bf16 v[94:97], v[66:69], v[200:203], v[94:97]
	v_mfma_f32_16x16x32_bf16 v[94:97], v[70:73], v[204:207], v[94:97]
	v_mfma_f32_16x16x32_bf16 v[66:69], v[66:69], v[208:211], v[86:89]
	v_mfma_f32_16x16x32_bf16 v[66:69], v[70:73], v[212:215], v[66:69]
	v_mfma_f32_16x16x32_bf16 v[106:109], v[74:77], v[178:181], v[106:109]
	v_mfma_f32_16x16x32_bf16 v[106:109], v[78:81], v[182:185], v[106:109]
	v_mfma_f32_16x16x32_bf16 v[98:101], v[74:77], v[192:195], v[98:101]
	v_mfma_f32_16x16x32_bf16 v[98:101], v[78:81], v[196:199], v[98:101]
	v_mfma_f32_16x16x32_bf16 v[90:93], v[74:77], v[200:203], v[90:93]
	v_mfma_f32_16x16x32_bf16 v[90:93], v[78:81], v[204:207], v[90:93]
	v_mfma_f32_16x16x32_bf16 v[70:73], v[74:77], v[208:211], v[82:85]
	v_mfma_f32_16x16x32_bf16 v[70:73], v[78:81], v[212:215], v[70:73]
	v_mfma_f32_16x16x32_bf16 v[30:33], v[146:149], v[178:181], v[30:33]
	v_mfma_f32_16x16x32_bf16 v[30:33], v[150:153], v[182:185], v[30:33]
	v_mfma_f32_16x16x32_bf16 v[22:25], v[146:149], v[192:195], v[22:25]
	v_mfma_f32_16x16x32_bf16 v[22:25], v[150:153], v[196:199], v[22:25]
	v_mfma_f32_16x16x32_bf16 v[14:17], v[146:149], v[200:203], v[14:17]
	v_mfma_f32_16x16x32_bf16 v[14:17], v[150:153], v[204:207], v[14:17]
	v_mfma_f32_16x16x32_bf16 v[6:9], v[146:149], v[208:211], v[6:9]
	v_mfma_f32_16x16x32_bf16 v[6:9], v[150:153], v[212:215], v[6:9]
	v_mfma_f32_16x16x32_bf16 v[26:29], v[154:157], v[178:181], v[26:29]
	v_mfma_f32_16x16x32_bf16 v[26:29], v[158:161], v[182:185], v[26:29]
	v_mfma_f32_16x16x32_bf16 v[18:21], v[154:157], v[192:195], v[18:21]
	v_mfma_f32_16x16x32_bf16 v[18:21], v[158:161], v[196:199], v[18:21]
	v_mfma_f32_16x16x32_bf16 v[10:13], v[154:157], v[200:203], v[10:13]
	v_mfma_f32_16x16x32_bf16 v[10:13], v[158:161], v[204:207], v[10:13]
	v_mfma_f32_16x16x32_bf16 v[2:5], v[154:157], v[208:211], v[2:5]
	v_mfma_f32_16x16x32_bf16 v[2:5], v[158:161], v[212:215], v[2:5]
	s_setprio 1
	s_barrier
; #define PG8_STAGE(bufoff, gbase, voff) do { const char* gb_ = (const char*)(gbase); asm volatile("" : "+s"(gb_)); _Pragma("unroll") for (int _i = 0; _i < 2; ++_i) { unsigned vo_ = (voff)[_i]; asm volatile("" : "+v"(vo_));        \
;         __builtin_amdgcn_global_load_lds((const unsigned*)(gb_ + vo_), (PG8_LAS unsigned*)(lds + (bufoff) + ldsw + _i * 8192), 16, 0, 0); } } while (0)
; #define PG8_LDA(dst, b, h) do { _Pragma("unroll") for (int m = 0; m < 4; ++m) _Pragma("unroll") for (int k = 0; k < 2; ++k) dst[m][k] = *(const PG8_LAS bf16x8*)(lds + PG8_SA(b, h) + aoff + m * 2048 + k * 1024); } while (0)
; #define PG8_LDB(dst, b, h) do { _Pragma("unroll") for (int n = 0; n < 2; ++n) _Pragma("unroll") for (int k = 0; k < 2; ++k) dst[n][k] = *(const PG8_LAS bf16x8*)(lds + PG8_SB(b, h) + boff + n * 2048 + k * 1024); } while (0)
; #define PG8_MMA(ai, bj, At, Bt) do { __builtin_amdgcn_s_setprio(1); _Pragma("unroll") for (int m = 0; m < 4; ++m) _Pragma("unroll") for (int n = 0; n < 2; ++n) _Pragma("unroll") for (int k = 0; k < 2; ++k) \
;         acc[ai][bj][m][n] = __builtin_amdgcn_mfma_f32_16x16x32_bf16(Bt[n][k], At[m][k], acc[ai][bj][m][n], 0, 0, 0); __builtin_amdgcn_s_setprio(0); } while (0)
; #define PG8_WAIT_V(n) asm volatile("s_waitcnt vmcnt(" #n ")" ::: "memory")
; #define PG8_WAIT_L(n) asm volatile("s_waitcnt lgkmcnt(" #n ")" ::: "memory")
; #define PG8_BAR __builtin_amdgcn_s_barrier()
; #define PG8_SCHED __builtin_amdgcn_sched_barrier(0)
; template <class Epi, class Sched, bool ALIGN_EPI = false, bool SP2 = false>
; __device__ __forceinline__ void gemm_phase(PG8_LAS unsigned char* lds, const Gemm g, const Sched& S, const Epi& E) {
;     ...
;             PG8_LDB(B0, 1, 0); PG8_LDB(B1, 1, 1); PG8_SCHED; PG8_LDA(At, 1, 0); PG8_STAGE(PG8_SA(0, 1), a2 + hstep, voffA);
;             PG8_WAIT_V(8); PG8_WAIT_L(0); PG8_BAR; PG8_MMA(0, 0, At, B0); PG8_MMA(0, 1, At, B1); PG8_BAR; PG8_SCHED;
;             PG8_LDA(At, 1, 1); PG8_STAGE(PG8_SB(1, 0), b3, voffB); PG8_STAGE(PG8_SB(1, 1), b3 + hstep, voffB); PG8_STAGE(PG8_SA(1, 0), a3, voffA);
;             PG8_WAIT_V(8); PG8_WAIT_L(0); PG8_BAR; PG8_MMA(1, 0, At, B0); PG8_MMA(1, 1, At, B1); PG8_BAR; PG8_SCHED;
;     ...
;         if constexpr (ALIGN_EPI) { if (wr == 0) PG8_BAR; }
	s_add_i32 s31, 0, 0x18000
	s_add_i32 s33, 0, 0x1c000
	ds_read_b128 v[74:77], v244 offset:32768
	ds_read_b128 v[78:81], v244 offset:33792
	ds_read_b128 v[82:85], v244 offset:34816
	ds_read_b128 v[146:149], v244 offset:35840
	ds_read_b128 v[150:153], v244 offset:49152
	ds_read_b128 v[154:157], v244 offset:50176
	ds_read_b128 v[158:161], v244 offset:51200
	ds_read_b128 v[178:181], v244 offset:52224
	s_add_u32 s0, s10, 0x80000
	s_addc_u32 s1, s11, 0
	s_mov_b32 m0, s15
	ds_read_b128 v[86:89], v223 offset:32768
	ds_read_b128 v[182:185], v223 offset:33792
	ds_read_b128 v[192:195], v223 offset:34816
	ds_read_b128 v[196:199], v223 offset:35840
	ds_read_b128 v[200:203], v223 offset:36864
	ds_read_b128 v[204:207], v223 offset:37888
	ds_read_b128 v[208:211], v223 offset:38912
	ds_read_b128 v[212:215], v223 offset:39936
	s_nop 0
	global_load_lds_dwordx4 v1, s[0:1]
	s_mov_b32 m0, s16
	s_nop 0
	global_load_lds_dwordx4 v191, s[0:1]
	s_waitcnt vmcnt(8)
	s_waitcnt lgkmcnt(0)
	s_barrier
	s_setprio 0
	s_waitcnt lgkmcnt(0)
	v_mfma_f32_16x16x32_bf16 v[142:145], v[74:77], v[86:89], v[142:145]
	v_mfma_f32_16x16x32_bf16 v[142:145], v[78:81], v[182:185], v[142:145]
	v_mfma_f32_16x16x32_bf16 v[134:137], v[74:77], v[192:195], v[134:137]
	v_mfma_f32_16x16x32_bf16 v[134:137], v[78:81], v[196:199], v[134:137]
	v_mfma_f32_16x16x32_bf16 v[126:129], v[74:77], v[200:203], v[126:129]
	v_mfma_f32_16x16x32_bf16 v[126:129], v[78:81], v[204:207], v[126:129]
	v_mfma_f32_16x16x32_bf16 v[118:121], v[74:77], v[208:211], v[118:121]
	v_mfma_f32_16x16x32_bf16 v[118:121], v[78:81], v[212:215], v[118:121]
	v_mfma_f32_16x16x32_bf16 v[138:141], v[82:85], v[86:89], v[138:141]
	v_mfma_f32_16x16x32_bf16 v[138:141], v[146:149], v[182:185], v[138:141]
	v_mfma_f32_16x16x32_bf16 v[130:133], v[82:85], v[192:195], v[130:133]
	v_mfma_f32_16x16x32_bf16 v[130:133], v[146:149], v[196:199], v[130:133]
	v_mfma_f32_16x16x32_bf16 v[122:125], v[82:85], v[200:203], v[122:125]
	v_mfma_f32_16x16x32_bf16 v[122:125], v[146:149], v[204:207], v[122:125]
	v_mfma_f32_16x16x32_bf16 v[114:117], v[82:85], v[208:211], v[114:117]
	v_mfma_f32_16x16x32_bf16 v[114:117], v[146:149], v[212:215], v[114:117]
	v_mfma_f32_16x16x32_bf16 v[62:65], v[150:153], v[86:89], v[62:65]
	v_mfma_f32_16x16x32_bf16 v[62:65], v[154:157], v[182:185], v[62:65]
	v_mfma_f32_16x16x32_bf16 v[54:57], v[150:153], v[192:195], v[54:57]
	v_mfma_f32_16x16x32_bf16 v[54:57], v[154:157], v[196:199], v[54:57]
	v_mfma_f32_16x16x32_bf16 v[46:49], v[150:153], v[200:203], v[46:49]
	v_mfma_f32_16x16x32_bf16 v[46:49], v[154:157], v[204:207], v[46:49]
	v_mfma_f32_16x16x32_bf16 v[38:41], v[150:153], v[208:211], v[38:41]
	v_mfma_f32_16x16x32_bf16 v[38:41], v[154:157], v[212:215], v[38:41]
	v_mfma_f32_16x16x32_bf16 v[58:61], v[158:161], v[86:89], v[58:61]
	v_mfma_f32_16x16x32_bf16 v[58:61], v[178:181], v[182:185], v[58:61]
	v_mfma_f32_16x16x32_bf16 v[50:53], v[158:161], v[192:195], v[50:53]
	v_mfma_f32_16x16x32_bf16 v[50:53], v[178:181], v[196:199], v[50:53]
	v_mfma_f32_16x16x32_bf16 v[42:45], v[158:161], v[200:203], v[42:45]
	v_mfma_f32_16x16x32_bf16 v[42:45], v[178:181], v[204:207], v[42:45]
	v_mfma_f32_16x16x32_bf16 v[34:37], v[158:161], v[208:211], v[34:37]
	v_mfma_f32_16x16x32_bf16 v[34:37], v[178:181], v[212:215], v[34:37]
	s_setprio 1
	s_barrier
	s_add_u32 s0, s8, 0x80
	s_addc_u32 s1, s9, 0
	s_add_i32 s10, s31, s12
	ds_read_b128 v[182:185], v223 offset:49152
	ds_read_b128 v[192:195], v223 offset:50176
	ds_read_b128 v[196:199], v223 offset:51200
	ds_read_b128 v[200:203], v223 offset:52224
	ds_read_b128 v[204:207], v223 offset:53248
	ds_read_b128 v[208:211], v223 offset:54272
	ds_read_b128 v[212:215], v223 offset:55296
	ds_read_b128 v[224:227], v223 offset:56320
	s_mov_b32 m0, s10
	s_nop 0
	global_load_lds_dwordx4 v189, s[0:1]
	s_add_i32 m0, s10, 0x2000
	s_nop 0
	global_load_lds_dwordx4 v219, s[0:1]
	s_add_u32 s0, s8, 0x80080
	s_addc_u32 s1, s9, 0
	s_add_i32 s8, s33, s12
	s_mov_b32 m0, s8
	s_nop 0
	global_load_lds_dwordx4 v189, s[0:1]
	s_add_i32 m0, s8, 0x2000
	s_nop 0
	global_load_lds_dwordx4 v219, s[0:1]
	s_mov_b32 m0, s19
	s_nop 0
	global_load_lds_dwordx4 v1, s[6:7]
	s_mov_b32 m0, s20
	s_nop 0
	global_load_lds_dwordx4 v191, s[6:7]
	s_waitcnt vmcnt(8)
	s_waitcnt lgkmcnt(0)
	s_barrier
	s_setprio 0
	s_waitcnt lgkmcnt(0)
	v_mfma_f32_16x16x32_bf16 v[86:89], v[74:77], v[182:185], v[110:113]
	v_mfma_f32_16x16x32_bf16 v[110:113], v[78:81], v[192:195], v[86:89]
	v_mfma_f32_16x16x32_bf16 v[66:69], v[74:77], v[212:215], v[66:69]
	v_mfma_f32_16x16x32_bf16 v[86:89], v[82:85], v[182:185], v[106:109]
	v_mfma_f32_16x16x32_bf16 v[106:109], v[146:149], v[192:195], v[86:89]
	v_mfma_f32_16x16x32_bf16 v[86:89], v[74:77], v[196:199], v[102:105]
	v_mfma_f32_16x16x32_bf16 v[102:105], v[78:81], v[200:203], v[86:89]
	v_mfma_f32_16x16x32_bf16 v[86:89], v[82:85], v[196:199], v[98:101]
	v_mfma_f32_16x16x32_bf16 v[98:101], v[146:149], v[200:203], v[86:89]
	v_mfma_f32_16x16x32_bf16 v[86:89], v[74:77], v[204:207], v[94:97]
	v_mfma_f32_16x16x32_bf16 v[94:97], v[78:81], v[208:211], v[86:89]
	v_mfma_f32_16x16x32_bf16 v[86:89], v[82:85], v[204:207], v[90:93]
	v_mfma_f32_16x16x32_bf16 v[90:93], v[146:149], v[208:211], v[86:89]
	v_mfma_f32_16x16x32_bf16 v[86:89], v[78:81], v[224:227], v[66:69]
	v_mfma_f32_16x16x32_bf16 v[66:69], v[82:85], v[212:215], v[70:73]
	v_mfma_f32_16x16x32_bf16 v[82:85], v[146:149], v[224:227], v[66:69]
	v_mfma_f32_16x16x32_bf16 v[30:33], v[150:153], v[182:185], v[30:33]
	v_mfma_f32_16x16x32_bf16 v[30:33], v[154:157], v[192:195], v[30:33]
	v_mfma_f32_16x16x32_bf16 v[22:25], v[150:153], v[196:199], v[22:25]
	v_mfma_f32_16x16x32_bf16 v[22:25], v[154:157], v[200:203], v[22:25]
	v_mfma_f32_16x16x32_bf16 v[14:17], v[150:153], v[204:207], v[14:17]
	v_mfma_f32_16x16x32_bf16 v[14:17], v[154:157], v[208:211], v[14:17]
	v_mfma_f32_16x16x32_bf16 v[6:9], v[150:153], v[212:215], v[6:9]
	v_mfma_f32_16x16x32_bf16 v[6:9], v[154:157], v[224:227], v[6:9]
	v_mfma_f32_16x16x32_bf16 v[26:29], v[158:161], v[182:185], v[26:29]
	v_mfma_f32_16x16x32_bf16 v[26:29], v[178:181], v[192:195], v[26:29]
	v_mfma_f32_16x16x32_bf16 v[18:21], v[158:161], v[196:199], v[18:21]
	v_mfma_f32_16x16x32_bf16 v[18:21], v[178:181], v[200:203], v[18:21]
	v_mfma_f32_16x16x32_bf16 v[10:13], v[158:161], v[204:207], v[10:13]
	v_mfma_f32_16x16x32_bf16 v[10:13], v[178:181], v[208:211], v[10:13]
	v_mfma_f32_16x16x32_bf16 v[2:5], v[158:161], v[212:215], v[2:5]
	v_mfma_f32_16x16x32_bf16 v[2:5], v[178:181], v[224:227], v[2:5]
	s_setprio 1
	s_barrier
	s_add_i32 s30, s30, 2
	s_add_u32 s28, s28, 0x100
	s_addc_u32 s29, s29, 0
	s_cmp_gt_u32 s30, 29
	s_mov_b64 s[0:1], s[2:3]
	s_cbranch_scc0 .LBB0_232
	s_and_b64 vcc, exec, s[44:45]
	s_cbranch_vccz .LBB0_235
	s_barrier

; #define PG8_STAGE(bufoff, gbase, voff) do { const char* gb_ = (const char*)(gbase); asm volatile("" : "+s"(gb_)); _Pragma("unroll") for (int _i = 0; _i < 2; ++_i) { unsigned vo_ = (voff)[_i]; asm volatile("" : "+v"(vo_));        \
;         __builtin_amdgcn_global_load_lds((const unsigned*)(gb_ + vo_), (PG8_LAS unsigned*)(lds + (bufoff) + ldsw + _i * 8192), 16, 0, 0); } } while (0)
; #define PG8_LDA(dst, b, h) do { _Pragma("unroll") for (int m = 0; m < 4; ++m) _Pragma("unroll") for (int k = 0; k < 2; ++k) dst[m][k] = *(const PG8_LAS bf16x8*)(lds + PG8_SA(b, h) + aoff + m * 2048 + k * 1024); } while (0)
; #define PG8_LDB(dst, b, h) do { _Pragma("unroll") for (int n = 0; n < 2; ++n) _Pragma("unroll") for (int k = 0; k < 2; ++k) dst[n][k] = *(const PG8_LAS bf16x8*)(lds + PG8_SB(b, h) + boff + n * 2048 + k * 1024); } while (0)
; #define PG8_MMA(ai, bj, At, Bt) do { __builtin_amdgcn_s_setprio(1); _Pragma("unroll") for (int m = 0; m < 4; ++m) _Pragma("unroll") for (int n = 0; n < 2; ++n) _Pragma("unroll") for (int k = 0; k < 2; ++k) \
;         acc[ai][bj][m][n] = __builtin_amdgcn_mfma_f32_16x16x32_bf16(Bt[n][k], At[m][k], acc[ai][bj][m][n], 0, 0, 0); __builtin_amdgcn_s_setprio(0); } while (0)
; #define PG8_WAIT_V(n) asm volatile("s_waitcnt vmcnt(" #n ")" ::: "memory")
; #define PG8_WAIT_L(n) asm volatile("s_waitcnt lgkmcnt(" #n ")" ::: "memory")
; #define PG8_BAR __builtin_amdgcn_s_barrier()
; #define PG8_SCHED __builtin_amdgcn_sched_barrier(0)
; template <class Epi, class Sched, bool ALIGN_EPI = false, bool SP2 = false>
; __device__ __forceinline__ void gemm_phase(PG8_LAS unsigned char* lds, const Gemm g, const Sched& S, const Epi& E) {
;     ...
;             PG8_LDB(B0, 0, 0); PG8_LDB(B1, 0, 1); PG8_SCHED; PG8_LDA(At, 0, 0); PG8_STAGE(PG8_SA(1, 1), a1 + hstep, voffA);
;             PG8_WAIT_V(8); PG8_WAIT_L(0); PG8_BAR; PG8_MMA(0, 0, At, B0); PG8_MMA(0, 1, At, B1); PG8_BAR; PG8_SCHED;
;             PG8_LDA(At, 0, 1); PG8_STAGE(PG8_SB(0, 0), b2, voffB); PG8_STAGE(PG8_SB(0, 1), b2 + hstep, voffB); PG8_STAGE(PG8_SA(0, 0), a2, voffA);
;             PG8_WAIT_V(8); PG8_WAIT_L(0); PG8_BAR; PG8_MMA(1, 0, At, B0); PG8_MMA(1, 1, At, B1); PG8_BAR; PG8_SCHED;
.LBB0_555:
	s_add_u32 s6, s4, 0x100
	s_addc_u32 s7, s5, 0
	s_cmp_eq_u32 s51, 28
	s_cselect_b32 s12, s35, s6
	s_cselect_b32 s13, s34, s7
	s_cselect_b32 s10, s39, s40
	s_cselect_b32 s11, s38, s49
	s_add_u32 s8, s12, 0x80
	s_addc_u32 s9, s13, 0
	s_add_i32 s56, 0, 0x10000
	s_add_i32 s57, 0, 0x14000
	ds_read_b128 v[26:29], v244
	ds_read_b128 v[30:33], v244 offset:1024
	ds_read_b128 v[98:101], v244 offset:2048
	ds_read_b128 v[102:105], v244 offset:3072
	ds_read_b128 v[146:149], v244 offset:16384
	ds_read_b128 v[150:153], v244 offset:17408
	ds_read_b128 v[154:157], v244 offset:18432
	ds_read_b128 v[158:161], v244 offset:19456
	s_add_u32 s4, s4, 0x80080
	s_addc_u32 s5, s5, 0
	ds_read_b128 v[178:181], v210
	ds_read_b128 v[182:185], v210 offset:1024
	ds_read_b128 v[186:189], v210 offset:2048
	ds_read_b128 v[190:193], v210 offset:3072
	ds_read_b128 v[194:197], v210 offset:4096
	ds_read_b128 v[198:201], v210 offset:5120
	ds_read_b128 v[202:205], v210 offset:6144
	ds_read_b128 v[212:215], v210 offset:7168
	s_add_i32 m0, s18, 0xc000
	s_nop 0
	global_load_lds_dwordx4 v1, s[4:5]
	s_add_i32 m0, s18, 0xe000
	s_nop 0
	global_load_lds_dwordx4 v164, s[4:5]
	s_waitcnt vmcnt(8)
	s_waitcnt lgkmcnt(0)
	s_barrier
	s_setprio 0
	s_waitcnt lgkmcnt(0)
	v_mfma_f32_16x16x32_bf16 v[142:145], v[26:29], v[178:181], v[142:145]
	v_mfma_f32_16x16x32_bf16 v[142:145], v[30:33], v[182:185], v[142:145]
	v_mfma_f32_16x16x32_bf16 v[134:137], v[26:29], v[186:189], v[134:137]
	v_mfma_f32_16x16x32_bf16 v[134:137], v[30:33], v[190:193], v[134:137]
	v_mfma_f32_16x16x32_bf16 v[126:129], v[26:29], v[194:197], v[126:129]
	v_mfma_f32_16x16x32_bf16 v[126:129], v[30:33], v[198:201], v[126:129]
	v_mfma_f32_16x16x32_bf16 v[118:121], v[26:29], v[202:205], v[118:121]
	v_mfma_f32_16x16x32_bf16 v[118:121], v[30:33], v[212:215], v[118:121]
	v_mfma_f32_16x16x32_bf16 v[138:141], v[98:101], v[178:181], v[138:141]
	v_mfma_f32_16x16x32_bf16 v[138:141], v[102:105], v[182:185], v[138:141]
	v_mfma_f32_16x16x32_bf16 v[130:133], v[98:101], v[186:189], v[130:133]
	v_mfma_f32_16x16x32_bf16 v[130:133], v[102:105], v[190:193], v[130:133]
	v_mfma_f32_16x16x32_bf16 v[122:125], v[98:101], v[194:197], v[122:125]
	v_mfma_f32_16x16x32_bf16 v[122:125], v[102:105], v[198:201], v[122:125]
	v_mfma_f32_16x16x32_bf16 v[114:117], v[98:101], v[202:205], v[114:117]
	v_mfma_f32_16x16x32_bf16 v[114:117], v[102:105], v[212:215], v[114:117]
	v_mfma_f32_16x16x32_bf16 v[70:73], v[146:149], v[178:181], v[70:73]
	v_mfma_f32_16x16x32_bf16 v[70:73], v[150:153], v[182:185], v[70:73]
	v_mfma_f32_16x16x32_bf16 v[62:65], v[146:149], v[186:189], v[62:65]
	v_mfma_f32_16x16x32_bf16 v[62:65], v[150:153], v[190:193], v[62:65]
	v_mfma_f32_16x16x32_bf16 v[54:57], v[146:149], v[194:197], v[54:57]
	v_mfma_f32_16x16x32_bf16 v[54:57], v[150:153], v[198:201], v[54:57]
	v_mfma_f32_16x16x32_bf16 v[46:49], v[146:149], v[202:205], v[46:49]
	v_mfma_f32_16x16x32_bf16 v[46:49], v[150:153], v[212:215], v[46:49]
	v_mfma_f32_16x16x32_bf16 v[66:69], v[154:157], v[178:181], v[66:69]
	v_mfma_f32_16x16x32_bf16 v[66:69], v[158:161], v[182:185], v[66:69]
	v_mfma_f32_16x16x32_bf16 v[58:61], v[154:157], v[186:189], v[58:61]
	v_mfma_f32_16x16x32_bf16 v[58:61], v[158:161], v[190:193], v[58:61]
	v_mfma_f32_16x16x32_bf16 v[50:53], v[154:157], v[194:197], v[50:53]
	v_mfma_f32_16x16x32_bf16 v[50:53], v[158:161], v[198:201], v[50:53]
	v_mfma_f32_16x16x32_bf16 v[42:45], v[154:157], v[202:205], v[42:45]
	v_mfma_f32_16x16x32_bf16 v[42:45], v[158:161], v[212:215], v[42:45]
	s_setprio 1
	s_barrier
	s_mov_b64 s[4:5], s[10:11]
	s_add_i32 s56, s56, s17
	ds_read_b128 v[178:181], v210 offset:16384
	ds_read_b128 v[182:185], v210 offset:17408
	ds_read_b128 v[186:189], v210 offset:18432
	ds_read_b128 v[190:193], v210 offset:19456
	ds_read_b128 v[194:197], v210 offset:20480
	ds_read_b128 v[198:201], v210 offset:21504
	ds_read_b128 v[202:205], v210 offset:22528
	ds_read_b128 v[212:215], v210 offset:23552
	s_mov_b32 m0, s56
	s_nop 0
	global_load_lds_dwordx4 v162, s[4:5]
	s_add_i32 m0, s56, 0x2000
	s_nop 0
	global_load_lds_dwordx4 v206, s[4:5]
	s_add_u32 s4, s10, 0x80000
	s_addc_u32 s5, s11, 0
	s_add_i32 s56, s57, s17
	s_mov_b32 m0, s56
	s_nop 0
	global_load_lds_dwordx4 v162, s[4:5]
	s_add_i32 m0, s56, 0x2000
	s_nop 0
	global_load_lds_dwordx4 v206, s[4:5]
	s_mov_b64 s[4:5], s[12:13]
	s_mov_b32 m0, s18
	s_nop 0
	global_load_lds_dwordx4 v1, s[4:5]
	s_mov_b32 m0, s19
	s_nop 0
	global_load_lds_dwordx4 v164, s[4:5]
	s_waitcnt vmcnt(8)
	s_waitcnt lgkmcnt(0)
	s_barrier
	s_setprio 0
	s_waitcnt lgkmcnt(0)
	v_mfma_f32_16x16x32_bf16 v[110:113], v[26:29], v[178:181], v[110:113]
	v_mfma_f32_16x16x32_bf16 v[110:113], v[30:33], v[182:185], v[110:113]
	v_mfma_f32_16x16x32_bf16 v[94:97], v[26:29], v[186:189], v[94:97]
	v_mfma_f32_16x16x32_bf16 v[94:97], v[30:33], v[190:193], v[94:97]
	v_mfma_f32_16x16x32_bf16 v[86:89], v[26:29], v[194:197], v[86:89]
	v_mfma_f32_16x16x32_bf16 v[86:89], v[30:33], v[198:201], v[86:89]
	v_mfma_f32_16x16x32_bf16 v[26:29], v[26:29], v[202:205], v[78:81]
	v_mfma_f32_16x16x32_bf16 v[26:29], v[30:33], v[212:215], v[26:29]
	v_mfma_f32_16x16x32_bf16 v[106:109], v[98:101], v[178:181], v[106:109]
	v_mfma_f32_16x16x32_bf16 v[106:109], v[102:105], v[182:185], v[106:109]
	v_mfma_f32_16x16x32_bf16 v[90:93], v[98:101], v[186:189], v[90:93]
	v_mfma_f32_16x16x32_bf16 v[90:93], v[102:105], v[190:193], v[90:93]
	v_mfma_f32_16x16x32_bf16 v[82:85], v[98:101], v[194:197], v[82:85]
	v_mfma_f32_16x16x32_bf16 v[82:85], v[102:105], v[198:201], v[82:85]
	v_mfma_f32_16x16x32_bf16 v[30:33], v[98:101], v[202:205], v[74:77]
	v_mfma_f32_16x16x32_bf16 v[30:33], v[102:105], v[212:215], v[30:33]
	v_mfma_f32_16x16x32_bf16 v[38:41], v[146:149], v[178:181], v[38:41]
	v_mfma_f32_16x16x32_bf16 v[38:41], v[150:153], v[182:185], v[38:41]
	v_mfma_f32_16x16x32_bf16 v[22:25], v[146:149], v[186:189], v[22:25]
	v_mfma_f32_16x16x32_bf16 v[22:25], v[150:153], v[190:193], v[22:25]
	v_mfma_f32_16x16x32_bf16 v[14:17], v[146:149], v[194:197], v[14:17]
	v_mfma_f32_16x16x32_bf16 v[14:17], v[150:153], v[198:201], v[14:17]
	v_mfma_f32_16x16x32_bf16 v[6:9], v[146:149], v[202:205], v[6:9]
	v_mfma_f32_16x16x32_bf16 v[6:9], v[150:153], v[212:215], v[6:9]
	v_mfma_f32_16x16x32_bf16 v[34:37], v[154:157], v[178:181], v[34:37]
	v_mfma_f32_16x16x32_bf16 v[34:37], v[158:161], v[182:185], v[34:37]
	v_mfma_f32_16x16x32_bf16 v[18:21], v[154:157], v[186:189], v[18:21]
	v_mfma_f32_16x16x32_bf16 v[18:21], v[158:161], v[190:193], v[18:21]
	v_mfma_f32_16x16x32_bf16 v[10:13], v[154:157], v[194:197], v[10:13]
	v_mfma_f32_16x16x32_bf16 v[10:13], v[158:161], v[198:201], v[10:13]
	v_mfma_f32_16x16x32_bf16 v[2:5], v[154:157], v[202:205], v[2:5]
	v_mfma_f32_16x16x32_bf16 v[2:5], v[158:161], v[212:215], v[2:5]
	s_setprio 1
	s_barrier
; #define PG8_STAGE(bufoff, gbase, voff) do { const char* gb_ = (const char*)(gbase); asm volatile("" : "+s"(gb_)); _Pragma("unroll") for (int _i = 0; _i < 2; ++_i) { unsigned vo_ = (voff)[_i]; asm volatile("" : "+v"(vo_));        \
;         __builtin_amdgcn_global_load_lds((const unsigned*)(gb_ + vo_), (PG8_LAS unsigned*)(lds + (bufoff) + ldsw + _i * 8192), 16, 0, 0); } } while (0)
; #define PG8_LDA(dst, b, h) do { _Pragma("unroll") for (int m = 0; m < 4; ++m) _Pragma("unroll") for (int k = 0; k < 2; ++k) dst[m][k] = *(const PG8_LAS bf16x8*)(lds + PG8_SA(b, h) + aoff + m * 2048 + k * 1024); } while (0)
; #define PG8_LDB(dst, b, h) do { _Pragma("unroll") for (int n = 0; n < 2; ++n) _Pragma("unroll") for (int k = 0; k < 2; ++k) dst[n][k] = *(const PG8_LAS bf16x8*)(lds + PG8_SB(b, h) + boff + n * 2048 + k * 1024); } while (0)
; #define PG8_MMA(ai, bj, At, Bt) do { __builtin_amdgcn_s_setprio(1); _Pragma("unroll") for (int m = 0; m < 4; ++m) _Pragma("unroll") for (int n = 0; n < 2; ++n) _Pragma("unroll") for (int k = 0; k < 2; ++k) \
;         acc[ai][bj][m][n] = __builtin_amdgcn_mfma_f32_16x16x32_bf16(Bt[n][k], At[m][k], acc[ai][bj][m][n], 0, 0, 0); __builtin_amdgcn_s_setprio(0); } while (0)
; #define PG8_WAIT_V(n) asm volatile("s_waitcnt vmcnt(" #n ")" ::: "memory")
; #define PG8_WAIT_L(n) asm volatile("s_waitcnt lgkmcnt(" #n ")" ::: "memory")
; #define PG8_BAR __builtin_amdgcn_s_barrier()
; #define PG8_SCHED __builtin_amdgcn_sched_barrier(0)
; template <class Epi, class Sched, bool ALIGN_EPI = false, bool SP2 = false>
; __device__ __forceinline__ void gemm_phase(PG8_LAS unsigned char* lds, const Gemm g, const Sched& S, const Epi& E) {
;     ...
;             PG8_LDB(B0, 1, 0); PG8_LDB(B1, 1, 1); PG8_SCHED; PG8_LDA(At, 1, 0); PG8_STAGE(PG8_SA(0, 1), a2 + hstep, voffA);
;             PG8_WAIT_V(8); PG8_WAIT_L(0); PG8_BAR; PG8_MMA(0, 0, At, B0); PG8_MMA(0, 1, At, B1); PG8_BAR; PG8_SCHED;
;             PG8_LDA(At, 1, 1); PG8_STAGE(PG8_SB(1, 0), b3, voffB); PG8_STAGE(PG8_SB(1, 1), b3 + hstep, voffB); PG8_STAGE(PG8_SA(1, 0), a3, voffA);
;             PG8_WAIT_V(8); PG8_WAIT_L(0); PG8_BAR; PG8_MMA(1, 0, At, B0); PG8_MMA(1, 1, At, B1); PG8_BAR; PG8_SCHED;
	s_add_i32 s56, 0, 0x18000
	s_add_i32 s57, 0, 0x1c000
	ds_read_b128 v[74:77], v244 offset:32768
	ds_read_b128 v[78:81], v244 offset:33792
	ds_read_b128 v[98:101], v244 offset:34816
	ds_read_b128 v[102:105], v244 offset:35840
	ds_read_b128 v[146:149], v244 offset:49152
	ds_read_b128 v[150:153], v244 offset:50176
	ds_read_b128 v[154:157], v244 offset:51200
	ds_read_b128 v[158:161], v244 offset:52224
	s_add_u32 s4, s12, 0x80000
	s_addc_u32 s5, s13, 0
	s_mov_b32 m0, s20
	ds_read_b128 v[178:181], v210 offset:32768
	ds_read_b128 v[182:185], v210 offset:33792
	ds_read_b128 v[186:189], v210 offset:34816
	ds_read_b128 v[190:193], v210 offset:35840
	ds_read_b128 v[194:197], v210 offset:36864
	ds_read_b128 v[198:201], v210 offset:37888
	ds_read_b128 v[202:205], v210 offset:38912
	ds_read_b128 v[212:215], v210 offset:39936
	s_nop 0
	global_load_lds_dwordx4 v1, s[4:5]
	s_mov_b32 m0, s21
	s_nop 0
	global_load_lds_dwordx4 v164, s[4:5]
	s_waitcnt vmcnt(8)
	s_waitcnt lgkmcnt(0)
	s_barrier
	s_setprio 0
	s_waitcnt lgkmcnt(0)
	v_mfma_f32_16x16x32_bf16 v[142:145], v[74:77], v[178:181], v[142:145]
	v_mfma_f32_16x16x32_bf16 v[142:145], v[78:81], v[182:185], v[142:145]
	v_mfma_f32_16x16x32_bf16 v[134:137], v[74:77], v[186:189], v[134:137]
	v_mfma_f32_16x16x32_bf16 v[134:137], v[78:81], v[190:193], v[134:137]
	v_mfma_f32_16x16x32_bf16 v[126:129], v[74:77], v[194:197], v[126:129]
	v_mfma_f32_16x16x32_bf16 v[126:129], v[78:81], v[198:201], v[126:129]
	v_mfma_f32_16x16x32_bf16 v[118:121], v[74:77], v[202:205], v[118:121]
	v_mfma_f32_16x16x32_bf16 v[118:121], v[78:81], v[212:215], v[118:121]
	v_mfma_f32_16x16x32_bf16 v[138:141], v[98:101], v[178:181], v[138:141]
	v_mfma_f32_16x16x32_bf16 v[138:141], v[102:105], v[182:185], v[138:141]
	v_mfma_f32_16x16x32_bf16 v[130:133], v[98:101], v[186:189], v[130:133]
	v_mfma_f32_16x16x32_bf16 v[130:133], v[102:105], v[190:193], v[130:133]
	v_mfma_f32_16x16x32_bf16 v[122:125], v[98:101], v[194:197], v[122:125]
	v_mfma_f32_16x16x32_bf16 v[122:125], v[102:105], v[198:201], v[122:125]
	v_mfma_f32_16x16x32_bf16 v[114:117], v[98:101], v[202:205], v[114:117]
	v_mfma_f32_16x16x32_bf16 v[114:117], v[102:105], v[212:215], v[114:117]
	v_mfma_f32_16x16x32_bf16 v[70:73], v[146:149], v[178:181], v[70:73]
	v_mfma_f32_16x16x32_bf16 v[70:73], v[150:153], v[182:185], v[70:73]
	v_mfma_f32_16x16x32_bf16 v[62:65], v[146:149], v[186:189], v[62:65]
	v_mfma_f32_16x16x32_bf16 v[62:65], v[150:153], v[190:193], v[62:65]
	v_mfma_f32_16x16x32_bf16 v[54:57], v[146:149], v[194:197], v[54:57]
	v_mfma_f32_16x16x32_bf16 v[54:57], v[150:153], v[198:201], v[54:57]
	v_mfma_f32_16x16x32_bf16 v[46:49], v[146:149], v[202:205], v[46:49]
	v_mfma_f32_16x16x32_bf16 v[46:49], v[150:153], v[212:215], v[46:49]
	v_mfma_f32_16x16x32_bf16 v[66:69], v[154:157], v[178:181], v[66:69]
	v_mfma_f32_16x16x32_bf16 v[66:69], v[158:161], v[182:185], v[66:69]
	v_mfma_f32_16x16x32_bf16 v[58:61], v[154:157], v[186:189], v[58:61]
	v_mfma_f32_16x16x32_bf16 v[58:61], v[158:161], v[190:193], v[58:61]
	v_mfma_f32_16x16x32_bf16 v[50:53], v[154:157], v[194:197], v[50:53]
	v_mfma_f32_16x16x32_bf16 v[50:53], v[158:161], v[198:201], v[50:53]
	v_mfma_f32_16x16x32_bf16 v[42:45], v[154:157], v[202:205], v[42:45]
	v_mfma_f32_16x16x32_bf16 v[42:45], v[158:161], v[212:215], v[42:45]
	s_setprio 1
	s_barrier
	s_add_u32 s4, s10, 0x80
	s_addc_u32 s5, s11, 0
	s_add_i32 s12, s56, s17
	ds_read_b128 v[178:181], v210 offset:49152
	ds_read_b128 v[182:185], v210 offset:50176
	ds_read_b128 v[186:189], v210 offset:51200
	ds_read_b128 v[190:193], v210 offset:52224
	ds_read_b128 v[194:197], v210 offset:53248
	ds_read_b128 v[198:201], v210 offset:54272
	ds_read_b128 v[202:205], v210 offset:55296
	ds_read_b128 v[212:215], v210 offset:56320
	s_mov_b32 m0, s12
	s_nop 0
	global_load_lds_dwordx4 v162, s[4:5]
	s_add_i32 m0, s12, 0x2000
	s_nop 0
	global_load_lds_dwordx4 v206, s[4:5]
	s_add_u32 s4, s10, 0x80080
	s_addc_u32 s5, s11, 0
	s_add_i32 s10, s57, s17
	s_mov_b32 m0, s10
	s_nop 0
	global_load_lds_dwordx4 v162, s[4:5]
	s_add_i32 m0, s10, 0x2000
	s_nop 0
	global_load_lds_dwordx4 v206, s[4:5]
	s_mov_b32 m0, s26
	s_nop 0
	global_load_lds_dwordx4 v1, s[8:9]
	s_mov_b32 m0, s27
	s_nop 0
	global_load_lds_dwordx4 v164, s[8:9]
	s_waitcnt vmcnt(8)
	s_waitcnt lgkmcnt(0)
	s_barrier
	s_setprio 0
	s_waitcnt lgkmcnt(0)
	v_mfma_f32_16x16x32_bf16 v[110:113], v[74:77], v[178:181], v[110:113]
	v_mfma_f32_16x16x32_bf16 v[110:113], v[78:81], v[182:185], v[110:113]
	v_mfma_f32_16x16x32_bf16 v[94:97], v[74:77], v[186:189], v[94:97]
	v_mfma_f32_16x16x32_bf16 v[94:97], v[78:81], v[190:193], v[94:97]
	v_mfma_f32_16x16x32_bf16 v[86:89], v[74:77], v[194:197], v[86:89]
	v_mfma_f32_16x16x32_bf16 v[86:89], v[78:81], v[198:201], v[86:89]
	v_mfma_f32_16x16x32_bf16 v[26:29], v[74:77], v[202:205], v[26:29]
	v_mfma_f32_16x16x32_bf16 v[78:81], v[78:81], v[212:215], v[26:29]
	v_mfma_f32_16x16x32_bf16 v[106:109], v[98:101], v[178:181], v[106:109]
	v_mfma_f32_16x16x32_bf16 v[106:109], v[102:105], v[182:185], v[106:109]
	v_mfma_f32_16x16x32_bf16 v[90:93], v[98:101], v[186:189], v[90:93]
	v_mfma_f32_16x16x32_bf16 v[90:93], v[102:105], v[190:193], v[90:93]
	v_mfma_f32_16x16x32_bf16 v[82:85], v[98:101], v[194:197], v[82:85]
	v_mfma_f32_16x16x32_bf16 v[82:85], v[102:105], v[198:201], v[82:85]
	v_mfma_f32_16x16x32_bf16 v[26:29], v[98:101], v[202:205], v[30:33]
	v_mfma_f32_16x16x32_bf16 v[74:77], v[102:105], v[212:215], v[26:29]
	v_mfma_f32_16x16x32_bf16 v[26:29], v[146:149], v[178:181], v[38:41]
	v_mfma_f32_16x16x32_bf16 v[38:41], v[150:153], v[182:185], v[26:29]
	v_mfma_f32_16x16x32_bf16 v[22:25], v[146:149], v[186:189], v[22:25]
	v_mfma_f32_16x16x32_bf16 v[22:25], v[150:153], v[190:193], v[22:25]
	v_mfma_f32_16x16x32_bf16 v[14:17], v[146:149], v[194:197], v[14:17]
	v_mfma_f32_16x16x32_bf16 v[14:17], v[150:153], v[198:201], v[14:17]
	v_mfma_f32_16x16x32_bf16 v[6:9], v[146:149], v[202:205], v[6:9]
	v_mfma_f32_16x16x32_bf16 v[6:9], v[150:153], v[212:215], v[6:9]
	v_mfma_f32_16x16x32_bf16 v[26:29], v[154:157], v[178:181], v[34:37]
	v_mfma_f32_16x16x32_bf16 v[34:37], v[158:161], v[182:185], v[26:29]
	v_mfma_f32_16x16x32_bf16 v[18:21], v[154:157], v[186:189], v[18:21]
	v_mfma_f32_16x16x32_bf16 v[18:21], v[158:161], v[190:193], v[18:21]
	v_mfma_f32_16x16x32_bf16 v[10:13], v[154:157], v[194:197], v[10:13]
	v_mfma_f32_16x16x32_bf16 v[10:13], v[158:161], v[198:201], v[10:13]
	v_mfma_f32_16x16x32_bf16 v[2:5], v[154:157], v[202:205], v[2:5]
	v_mfma_f32_16x16x32_bf16 v[2:5], v[158:161], v[212:215], v[2:5]
	s_setprio 1
	s_barrier
;     __device__ __forceinline__ void operator()(const f32x4 (&acc)[2][2][4][2], const Unit& u, int wr, int wc, int fr, int fq) const {
;         const int row0 = u.pm * BM + wr * 64 + fr, col0 = u.pn * BM + wc * 32 + 8 * fq, b = (u.pm * BM) / rows_per_batch;
;         const float* g = gate + (size_t)b * gate_bstride + col0;
;         float ssq[2][4];
; #pragma unroll
;         for (int ai = 0; ai < 2; ++ai)
; #pragma unroll
;             for (int m = 0; m < 4; ++m) ssq[ai][m] = 0.f;
;         f32x4 gv[2][2], Gv[2][2];
; #pragma unroll
;         for (int bj = 0; bj < 2; ++bj) { gv[bj][0] = *(const f32x4*)(g + bj * HALF); gv[bj][1] = *(const f32x4*)(g + bj * HALF + 4); Gv[bj][0] = (f32x4){0.f, 0.f, 0.f, 0.f}; Gv[bj][1] = (f32x4){0.f, 0.f, 0.f, 0.f};
;             if (Hn) { const float* sc = scnext + (size_t)b * gate_bstride + col0 + bj * HALF;
;                 Gv[bj][0] = *(const f32x4*)(gnext + col0 + bj * HALF) * (1.0f + *(const f32x4*)(sc)); Gv[bj][1] = *(const f32x4*)(gnext + col0 + bj * HALF + 4) * (1.0f + *(const f32x4*)(sc + 4)); } }
; #pragma unroll
;         for (int bj = 0; bj < 2; ++bj) {
;             const f32x4 g0 = gv[bj][0], g1 = gv[bj][1], G0 = Gv[bj][0], G1 = Gv[bj][1];
; #pragma unroll
;             for (int ai = 0; ai < 2; ++ai)
; #pragma unroll
;                 for (int m = 0; m < 4; ++m) { const size_t off = (size_t)(row0 + ai * HALF + m * 16) * 2048 + col0 + bj * HALF;
;                     f32x4 x0 = __builtin_nontemporal_load((const f32x4*)(base + off)), x1 = __builtin_nontemporal_load((const f32x4*)(base + off + 4));
;                     if constexpr (HAS_DIN) { const u32x4 dw = __builtin_nontemporal_load((const u32x4*)(dbuf + off));
;                         x0 += (f32x4){__builtin_bit_cast(float, dw.x << 16), __builtin_bit_cast(float, dw.x & 0xffff0000u), __builtin_bit_cast(float, dw.y << 16), __builtin_bit_cast(float, dw.y & 0xffff0000u)};
;                         x1 += (f32x4){__builtin_bit_cast(float, dw.z << 16), __builtin_bit_cast(float, dw.z & 0xffff0000u), __builtin_bit_cast(float, dw.w << 16), __builtin_bit_cast(float, dw.w & 0xffff0000u)}; }
;                     f32x4 o0, o1;
;                     if constexpr (OUT_DELTA) { const f32x4 d0 = g0 * acc[ai][bj][m][0], d1 = g1 * acc[ai][bj][m][1];
	s_add_i32 s51, s51, 2
	s_add_u32 s40, s40, 0x100
	s_addc_u32 s49, s49, 0
	s_cmp_gt_u32 s51, 29
	s_mov_b64 s[4:5], s[6:7]
	s_cbranch_scc0 .LBB0_555
	s_ashr_i32 s4, s29, 31
	s_lshr_b32 s4, s4, 27
	s_add_i32 s4, s29, s4
	s_ashr_i32 s4, s4, 5
	v_lshl_or_b32 v148, s33, 8, v209
	s_mul_i32 s7, s4, 0xc000
	v_ashrrev_i32_e32 v149, 31, v148
	s_mul_hi_i32 s6, s4, 0xc000
	s_add_u32 s4, s22, s7
	s_addc_u32 s5, s23, s6
	v_lshlrev_b64 v[26:27], 2, v[148:149]
	v_lshl_add_u64 v[146:147], s[4:5], 0, v[26:27]
	s_add_u32 s4, s24, s7
	s_addc_u32 s5, s25, s6
	v_lshl_add_u64 v[160:161], s[4:5], 0, v[26:27]
	v_lshl_add_u64 v[178:179], s[46:47], 0, v[26:27]
	global_load_dwordx4 v[98:101], v[146:147], off offset:16
	global_load_dwordx4 v[102:105], v[146:147], off
	global_load_dwordx4 v[26:29], v[178:179], off offset:16
	global_load_dwordx4 v[30:33], v[178:179], off
	global_load_dwordx4 v[150:153], v[160:161], off offset:16
	global_load_dwordx4 v[154:157], v[160:161], off
	s_mov_b64 s[4:5], 0x40000
	s_waitcnt vmcnt(0)
	v_pk_mul_f32 v[188:189], v[140:141], v[100:101]
	v_pk_mul_f32 v[142:143], v[142:143], v[102:103]
	v_pk_mul_f32 v[144:145], v[144:145], v[104:105]
	v_pk_mul_f32 v[140:141], v[138:139], v[98:99]
	v_pk_mul_f32 v[136:137], v[136:137], v[104:105]
	v_pk_add_f32 v[156:157], v[156:157], 1.0 op_sel_hi:[1,0]
	v_pk_add_f32 v[154:155], v[154:155], 1.0 op_sel_hi:[1,0]
	v_pk_mul_f32 v[198:199], v[32:33], v[156:157]
	v_pk_mul_f32 v[200:201], v[30:31], v[154:155]
	v_pk_add_f32 v[30:31], v[152:153], 1.0 op_sel_hi:[1,0]
	v_pk_add_f32 v[32:33], v[150:151], 1.0 op_sel_hi:[1,0]
	v_pk_mul_f32 v[202:203], v[28:29], v[30:31]
	v_pk_mul_f32 v[204:205], v[26:27], v[32:33]
	global_load_dwordx4 v[26:29], v[146:147], off offset:528
	global_load_dwordx4 v[30:33], v[146:147], off offset:512
	global_load_dwordx4 v[156:159], v[178:179], off offset:528
	global_load_dwordx4 v[152:155], v[178:179], off offset:512
	s_nop 0
	global_load_dwordx4 v[178:181], v[160:161], off offset:528
	global_load_dwordx4 v[182:185], v[160:161], off offset:512
	v_pk_mul_f32 v[134:135], v[134:135], v[102:103]
	v_pk_mul_f32 v[130:131], v[130:131], v[98:99]
	v_pk_mul_f32 v[132:133], v[132:133], v[100:101]
	v_pk_mul_f32 v[128:129], v[128:129], v[104:105]
	v_pk_mul_f32 v[126:127], v[126:127], v[102:103]
	v_pk_mul_f32 v[122:123], v[122:123], v[98:99]
	v_pk_mul_f32 v[124:125], v[124:125], v[100:101]
	v_pk_mul_f32 v[120:121], v[120:121], v[104:105]
	v_pk_mul_f32 v[118:119], v[118:119], v[102:103]
	v_pk_mul_f32 v[114:115], v[114:115], v[98:99]
	v_pk_mul_f32 v[116:117], v[116:117], v[100:101]
	v_pk_mul_f32 v[112:113], v[112:113], v[104:105]
	v_pk_mul_f32 v[110:111], v[110:111], v[102:103]
	v_pk_mul_f32 v[106:107], v[106:107], v[98:99]
	v_pk_mul_f32 v[108:109], v[108:109], v[100:101]
	v_pk_mul_f32 v[96:97], v[96:97], v[104:105]
	v_pk_mul_f32 v[94:95], v[94:95], v[102:103]
	v_pk_mul_f32 v[90:91], v[90:91], v[98:99]
	v_pk_mul_f32 v[92:93], v[92:93], v[100:101]
	v_pk_mul_f32 v[88:89], v[88:89], v[104:105]
	v_pk_mul_f32 v[86:87], v[86:87], v[102:103]
	v_pk_mul_f32 v[82:83], v[82:83], v[98:99]
	v_pk_mul_f32 v[84:85], v[84:85], v[100:101]
	v_pk_mul_f32 v[80:81], v[80:81], v[104:105]
	v_pk_mul_f32 v[78:79], v[78:79], v[102:103]
	v_pk_mul_f32 v[74:75], v[74:75], v[98:99]
	v_pk_mul_f32 v[76:77], v[76:77], v[100:101]
	s_waitcnt vmcnt(5)
	v_pk_mul_f32 v[58:59], v[58:59], v[26:27]
	s_waitcnt vmcnt(4)
	v_pk_mul_f32 v[72:73], v[72:73], v[32:33]
	v_pk_mul_f32 v[70:71], v[70:71], v[30:31]
	v_pk_mul_f32 v[64:65], v[64:65], v[32:33]
	v_pk_mul_f32 v[62:63], v[62:63], v[30:31]
	s_waitcnt vmcnt(0)
	v_pk_add_f32 v[146:147], v[184:185], 1.0 op_sel_hi:[1,0]
	v_pk_add_f32 v[160:161], v[182:183], 1.0 op_sel_hi:[1,0]
	v_pk_mul_f32 v[150:151], v[154:155], v[146:147]
	v_pk_add_f32 v[146:147], v[180:181], 1.0 op_sel_hi:[1,0]
	v_pk_mul_f32 v[152:153], v[152:153], v[160:161]
	v_pk_mul_f32 v[154:155], v[158:159], v[146:147]
	v_lshl_add_u32 v146, s29, 8, v207
	v_ashrrev_i32_e32 v147, 31, v146
	v_lshlrev_b64 v[184:185], 11, v[146:147]
	v_lshl_add_u64 v[186:187], v[184:185], 0, v[148:149]
	v_pk_add_f32 v[160:161], v[178:179], 1.0 op_sel_hi:[1,0]
	v_lshl_add_u64 v[178:179], v[186:187], 2, s[44:45]
	v_pk_mul_f32 v[156:157], v[156:157], v[160:161]
	global_load_dwordx4 v[158:161], v[178:179], off nt
	global_load_dwordx4 v[180:183], v[178:179], off offset:16 nt
	v_cvt_pk_bf16_f32 v138, v142, v143
	v_lshlrev_b64 v[142:143], 1, v[186:187]
	v_cvt_pk_bf16_f32 v139, v144, v145
	v_cvt_pk_bf16_f32 v140, v140, v141
	v_cvt_pk_bf16_f32 v141, v188, v189
	v_lshl_add_u64 v[144:145], s[90:91], 0, v[142:143]
	global_store_dwordx4 v[144:145], v[138:141], off
	v_lshlrev_b32_e32 v144, 16, v140
	v_and_b32_e32 v145, 0xffff0000, v140
	v_lshlrev_b32_e32 v140, 16, v141
	v_and_b32_e32 v141, 0xffff0000, v141
	v_lshl_add_u64 v[142:143], s[96:97], 0, v[142:143]
	v_pk_mul_f32 v[60:61], v[60:61], v[28:29]
	v_pk_mul_f32 v[56:57], v[56:57], v[32:33]
	v_pk_mul_f32 v[54:55], v[54:55], v[30:31]
	v_pk_mul_f32 v[50:51], v[50:51], v[26:27]
	v_pk_mul_f32 v[52:53], v[52:53], v[28:29]
	v_pk_mul_f32 v[48:49], v[48:49], v[32:33]
	v_pk_mul_f32 v[46:47], v[46:47], v[30:31]
	v_pk_mul_f32 v[42:43], v[42:43], v[26:27]
	v_pk_mul_f32 v[44:45], v[44:45], v[28:29]
	v_pk_mul_f32 v[40:41], v[40:41], v[32:33]
	v_pk_mul_f32 v[38:39], v[38:39], v[30:31]
	v_pk_mul_f32 v[34:35], v[34:35], v[26:27]
	v_pk_mul_f32 v[36:37], v[36:37], v[28:29]
	v_pk_mul_f32 v[24:25], v[24:25], v[32:33]
	v_pk_mul_f32 v[22:23], v[22:23], v[30:31]
	v_pk_mul_f32 v[18:19], v[18:19], v[26:27]
	v_pk_mul_f32 v[20:21], v[20:21], v[28:29]
	v_pk_mul_f32 v[16:17], v[16:17], v[32:33]
	v_pk_mul_f32 v[14:15], v[14:15], v[30:31]
	v_pk_mul_f32 v[10:11], v[10:11], v[26:27]
	v_pk_mul_f32 v[12:13], v[12:13], v[28:29]
	v_pk_mul_f32 v[8:9], v[8:9], v[32:33]
	v_pk_mul_f32 v[6:7], v[6:7], v[30:31]
	v_pk_mul_f32 v[2:3], v[2:3], v[26:27]
	v_pk_mul_f32 v[4:5], v[4:5], v[28:29]
	s_waitcnt vmcnt(1)
; __device__ __forceinline__ unsigned cvt_pk_bf16(float lo, float hi) { unsigned r; asm volatile("v_cvt_pk_bf16_f32 %0, %1, %2" : "=v"(r) : "v"(lo), "v"(hi)); return r; }
;     __device__ __forceinline__ void operator()(const f32x4 (&acc)[2][2][4][2], const Unit& u, int wr, int wc, int fr, int fq) const {
;     ...
;                 for (int m = 0; m < 4; ++m) { const size_t off = (size_t)(row0 + ai * HALF + m * 16) * 2048 + col0 + bj * HALF;
;                     f32x4 x0 = __builtin_nontemporal_load((const f32x4*)(base + off)), x1 = __builtin_nontemporal_load((const f32x4*)(base + off + 4));
;                     if constexpr (HAS_DIN) { const u32x4 dw = __builtin_nontemporal_load((const u32x4*)(dbuf + off));
;                         x0 += (f32x4){__builtin_bit_cast(float, dw.x << 16), __builtin_bit_cast(float, dw.x & 0xffff0000u), __builtin_bit_cast(float, dw.y << 16), __builtin_bit_cast(float, dw.y & 0xffff0000u)};
;                         x1 += (f32x4){__builtin_bit_cast(float, dw.z << 16), __builtin_bit_cast(float, dw.z & 0xffff0000u), __builtin_bit_cast(float, dw.w << 16), __builtin_bit_cast(float, dw.w & 0xffff0000u)}; }
;                     f32x4 o0, o1;
;                     if constexpr (OUT_DELTA) { const f32x4 d0 = g0 * acc[ai][bj][m][0], d1 = g1 * acc[ai][bj][m][1];
;                         u32x4 w; w.x = cvt_pk_bf16(d0[0], d0[1]); w.y = cvt_pk_bf16(d0[2], d0[3]); w.z = cvt_pk_bf16(d1[0], d1[1]); w.w = cvt_pk_bf16(d1[2], d1[3]);
;                         *(u32x4*)(dbuf + off) = w;
;                         o0 = x0 + (f32x4){__builtin_bit_cast(float, w.x << 16), __builtin_bit_cast(float, w.x & 0xffff0000u), __builtin_bit_cast(float, w.y << 16), __builtin_bit_cast(float, w.y & 0xffff0000u)};
;                         o1 = x1 + (f32x4){__builtin_bit_cast(float, w.z << 16), __builtin_bit_cast(float, w.z & 0xffff0000u), __builtin_bit_cast(float, w.w << 16), __builtin_bit_cast(float, w.w & 0xffff0000u)}; }
;                     else { o0 = x0 + g0 * acc[ai][bj][m][0]; o1 = x1 + g1 * acc[ai][bj][m][1]; *(f32x4*)(out + off) = o0; *(f32x4*)(out + off + 4) = o1; }
;                     if (Hn) { const f32x4 h0 = o0 * G0, h1 = o1 * G1;
;                         u32x4 w; w.x = cvt_pk_bf16(h0[0], h0[1]); w.y = cvt_pk_bf16(h0[2], h0[3]); w.z = cvt_pk_bf16(h1[0], h1[1]); w.w = cvt_pk_bf16(h1[2], h1[3]);
;                         *(u32x4*)(Hn + off) = w;
	v_pk_add_f32 v[182:183], v[182:183], v[140:141]
	v_lshlrev_b32_e32 v140, 16, v138
	v_and_b32_e32 v141, 0xffff0000, v138
	v_lshlrev_b32_e32 v138, 16, v139
	v_and_b32_e32 v139, 0xffff0000, v139
	v_pk_add_f32 v[158:159], v[158:159], v[140:141]
	v_pk_add_f32 v[160:161], v[160:161], v[138:139]
	v_pk_mul_f32 v[138:139], v[200:201], v[158:159]
	v_pk_add_f32 v[144:145], v[180:181], v[144:145]
	v_pk_mul_f32 v[140:141], v[198:199], v[160:161]
	v_cvt_pk_bf16_f32 v138, v138, v139
	v_pk_mul_f32 v[180:181], v[202:203], v[182:183]
	v_cvt_pk_bf16_f32 v139, v140, v141
	v_pk_mul_f32 v[186:187], v[204:205], v[144:145]
	s_nop 0
	v_cvt_pk_bf16_f32 v140, v186, v187
	v_cvt_pk_bf16_f32 v141, v180, v181
	global_store_dwordx4 v[142:143], v[138:141], off
	s_nop 1
	v_mul_f32_e32 v138, v159, v159
	v_mul_f32_e32 v139, v161, v161
	v_fmac_f32_e32 v138, v158, v158
	v_fmac_f32_e32 v139, v160, v160
	v_add_f32_e32 v138, v138, v139
	v_mul_f32_e32 v139, v145, v145
	v_mul_f32_e32 v140, v183, v183
	v_fmac_f32_e32 v139, v144, v144
	v_fmac_f32_e32 v140, v182, v182
	v_add_f32_e32 v139, v139, v140
	v_add_f32_e32 v211, v138, v139
	v_or_b32_e32 v138, 16, v146
	v_ashrrev_i32_e32 v139, 31, v138
	v_lshlrev_b64 v[140:141], 11, v[138:139]
	v_lshl_add_u64 v[180:181], v[140:141], 0, v[148:149]
	v_lshl_add_u64 v[138:139], v[180:181], 2, s[44:45]
	global_load_dwordx4 v[142:145], v[138:139], off nt
	global_load_dwordx4 v[158:161], v[138:139], off offset:16 nt
	v_lshlrev_b64 v[180:181], 1, v[180:181]
	v_cvt_pk_bf16_f32 v134, v134, v135
	v_cvt_pk_bf16_f32 v135, v136, v137
	v_cvt_pk_bf16_f32 v136, v130, v131
	v_cvt_pk_bf16_f32 v137, v132, v133
	v_lshl_add_u64 v[130:131], s[90:91], 0, v[180:181]
	global_store_dwordx4 v[130:131], v[134:137], off
	v_lshlrev_b32_e32 v132, 16, v136
	v_and_b32_e32 v133, 0xffff0000, v136
	v_lshlrev_b32_e32 v130, 16, v137
	v_and_b32_e32 v131, 0xffff0000, v137
	v_lshlrev_b32_e32 v136, 16, v134
	v_and_b32_e32 v137, 0xffff0000, v134
	v_lshlrev_b32_e32 v134, 16, v135
	v_and_b32_e32 v135, 0xffff0000, v135
	s_waitcnt vmcnt(2)
	v_pk_add_f32 v[134:135], v[144:145], v[134:135]
	s_waitcnt vmcnt(1)
	v_pk_add_f32 v[130:131], v[160:161], v[130:131]
	v_pk_add_f32 v[136:137], v[142:143], v[136:137]
	v_pk_add_f32 v[132:133], v[158:159], v[132:133]
	v_pk_mul_f32 v[144:145], v[198:199], v[134:135]
	v_pk_mul_f32 v[142:143], v[200:201], v[136:137]
	v_pk_mul_f32 v[158:159], v[202:203], v[130:131]
	v_pk_mul_f32 v[160:161], v[204:205], v[132:133]
	v_cvt_pk_bf16_f32 v142, v142, v143
	v_cvt_pk_bf16_f32 v143, v144, v145
	s_nop 0
	v_cvt_pk_bf16_f32 v144, v160, v161
	v_cvt_pk_bf16_f32 v145, v158, v159
	v_lshl_add_u64 v[158:159], s[96:97], 0, v[180:181]
	global_store_dwordx4 v[158:159], v[142:145], off
	s_nop 1
	v_or_b32_e32 v142, 32, v146
	v_ashrrev_i32_e32 v143, 31, v142
	v_lshlrev_b64 v[144:145], 11, v[142:143]
	v_lshl_add_u64 v[186:187], v[144:145], 0, v[148:149]
	v_lshl_add_u64 v[142:143], v[186:187], 2, s[44:45]
	global_load_dwordx4 v[158:161], v[142:143], off nt
	global_load_dwordx4 v[180:183], v[142:143], off offset:16 nt
	v_lshlrev_b64 v[186:187], 1, v[186:187]
	v_cvt_pk_bf16_f32 v126, v126, v127
	v_cvt_pk_bf16_f32 v127, v128, v129
	v_cvt_pk_bf16_f32 v128, v122, v123
	v_cvt_pk_bf16_f32 v129, v124, v125
	v_lshl_add_u64 v[122:123], s[90:91], 0, v[186:187]
	global_store_dwordx4 v[122:123], v[126:129], off
	v_lshlrev_b32_e32 v124, 16, v128
	v_and_b32_e32 v125, 0xffff0000, v128
	v_lshlrev_b32_e32 v122, 16, v129
	v_and_b32_e32 v123, 0xffff0000, v129
	v_lshlrev_b32_e32 v128, 16, v126
	v_and_b32_e32 v129, 0xffff0000, v126
	v_lshlrev_b32_e32 v126, 16, v127
	v_and_b32_e32 v127, 0xffff0000, v127
	s_waitcnt vmcnt(2)
	v_pk_add_f32 v[126:127], v[160:161], v[126:127]
	s_waitcnt vmcnt(1)
	v_pk_add_f32 v[122:123], v[182:183], v[122:123]
	v_pk_add_f32 v[128:129], v[158:159], v[128:129]
	v_pk_add_f32 v[124:125], v[180:181], v[124:125]
	v_pk_mul_f32 v[160:161], v[198:199], v[126:127]
	v_pk_mul_f32 v[158:159], v[200:201], v[128:129]
	v_pk_mul_f32 v[180:181], v[202:203], v[122:123]
	v_pk_mul_f32 v[182:183], v[204:205], v[124:125]
	v_cvt_pk_bf16_f32 v158, v158, v159
	v_cvt_pk_bf16_f32 v159, v160, v161
	s_nop 0
	v_cvt_pk_bf16_f32 v160, v182, v183
	v_cvt_pk_bf16_f32 v161, v180, v181
	v_lshl_add_u64 v[180:181], s[96:97], 0, v[186:187]
	global_store_dwordx4 v[180:181], v[158:161], off
	s_nop 1
	v_or_b32_e32 v158, 48, v146
	v_ashrrev_i32_e32 v159, 31, v158
	v_lshlrev_b64 v[160:161], 11, v[158:159]
	v_lshl_add_u64 v[190:191], v[160:161], 0, v[148:149]
	v_lshl_add_u64 v[158:159], v[190:191], 2, s[44:45]
	global_load_dwordx4 v[180:183], v[158:159], off nt
	global_load_dwordx4 v[186:189], v[158:159], off offset:16 nt
	v_lshlrev_b64 v[190:191], 1, v[190:191]
	v_cvt_pk_bf16_f32 v118, v118, v119
	v_cvt_pk_bf16_f32 v119, v120, v121
	v_cvt_pk_bf16_f32 v120, v114, v115
	v_cvt_pk_bf16_f32 v121, v116, v117
	v_lshl_add_u64 v[114:115], s[90:91], 0, v[190:191]
	global_store_dwordx4 v[114:115], v[118:121], off
	v_lshlrev_b32_e32 v116, 16, v120
	v_and_b32_e32 v117, 0xffff0000, v120
	v_lshlrev_b32_e32 v114, 16, v121
	v_and_b32_e32 v115, 0xffff0000, v121
	v_lshlrev_b32_e32 v120, 16, v118
	v_and_b32_e32 v121, 0xffff0000, v118
	v_lshlrev_b32_e32 v118, 16, v119
	v_and_b32_e32 v119, 0xffff0000, v119
	s_waitcnt vmcnt(2)
	v_pk_add_f32 v[118:119], v[182:183], v[118:119]
	s_waitcnt vmcnt(1)
; __device__ __forceinline__ unsigned cvt_pk_bf16(float lo, float hi) { unsigned r; asm volatile("v_cvt_pk_bf16_f32 %0, %1, %2" : "=v"(r) : "v"(lo), "v"(hi)); return r; }
;     __device__ __forceinline__ void operator()(const f32x4 (&acc)[2][2][4][2], const Unit& u, int wr, int wc, int fr, int fq) const {
;     ...
;                 for (int m = 0; m < 4; ++m) { const size_t off = (size_t)(row0 + ai * HALF + m * 16) * 2048 + col0 + bj * HALF;
;                     f32x4 x0 = __builtin_nontemporal_load((const f32x4*)(base + off)), x1 = __builtin_nontemporal_load((const f32x4*)(base + off + 4));
;                     if constexpr (HAS_DIN) { const u32x4 dw = __builtin_nontemporal_load((const u32x4*)(dbuf + off));
;                         x0 += (f32x4){__builtin_bit_cast(float, dw.x << 16), __builtin_bit_cast(float, dw.x & 0xffff0000u), __builtin_bit_cast(float, dw.y << 16), __builtin_bit_cast(float, dw.y & 0xffff0000u)};
;                         x1 += (f32x4){__builtin_bit_cast(float, dw.z << 16), __builtin_bit_cast(float, dw.z & 0xffff0000u), __builtin_bit_cast(float, dw.w << 16), __builtin_bit_cast(float, dw.w & 0xffff0000u)}; }
;                     f32x4 o0, o1;
;                     if constexpr (OUT_DELTA) { const f32x4 d0 = g0 * acc[ai][bj][m][0], d1 = g1 * acc[ai][bj][m][1];
;                         u32x4 w; w.x = cvt_pk_bf16(d0[0], d0[1]); w.y = cvt_pk_bf16(d0[2], d0[3]); w.z = cvt_pk_bf16(d1[0], d1[1]); w.w = cvt_pk_bf16(d1[2], d1[3]);
;                         *(u32x4*)(dbuf + off) = w;
;                         o0 = x0 + (f32x4){__builtin_bit_cast(float, w.x << 16), __builtin_bit_cast(float, w.x & 0xffff0000u), __builtin_bit_cast(float, w.y << 16), __builtin_bit_cast(float, w.y & 0xffff0000u)};
;                         o1 = x1 + (f32x4){__builtin_bit_cast(float, w.z << 16), __builtin_bit_cast(float, w.z & 0xffff0000u), __builtin_bit_cast(float, w.w << 16), __builtin_bit_cast(float, w.w & 0xffff0000u)}; }
;                     else { o0 = x0 + g0 * acc[ai][bj][m][0]; o1 = x1 + g1 * acc[ai][bj][m][1]; *(f32x4*)(out + off) = o0; *(f32x4*)(out + off + 4) = o1; }
;                     if (Hn) { const f32x4 h0 = o0 * G0, h1 = o1 * G1;
;                         u32x4 w; w.x = cvt_pk_bf16(h0[0], h0[1]); w.y = cvt_pk_bf16(h0[2], h0[3]); w.z = cvt_pk_bf16(h1[0], h1[1]); w.w = cvt_pk_bf16(h1[2], h1[3]);
;                         *(u32x4*)(Hn + off) = w;
	v_pk_add_f32 v[114:115], v[188:189], v[114:115]
	v_pk_add_f32 v[120:121], v[180:181], v[120:121]
	v_pk_add_f32 v[116:117], v[186:187], v[116:117]
	v_pk_mul_f32 v[182:183], v[198:199], v[118:119]
	v_pk_mul_f32 v[180:181], v[200:201], v[120:121]
	v_pk_mul_f32 v[186:187], v[202:203], v[114:115]
	v_pk_mul_f32 v[188:189], v[204:205], v[116:117]
	v_cvt_pk_bf16_f32 v180, v180, v181
	v_cvt_pk_bf16_f32 v181, v182, v183
	s_nop 0
	v_cvt_pk_bf16_f32 v182, v188, v189
	v_cvt_pk_bf16_f32 v183, v186, v187
	v_lshl_add_u64 v[186:187], s[96:97], 0, v[190:191]
	global_store_dwordx4 v[186:187], v[180:183], off
	s_nop 1
	v_lshl_add_u64 v[182:183], v[184:185], 0, s[4:5]
	v_lshl_add_u64 v[194:195], v[182:183], 0, v[148:149]
	v_lshl_add_u64 v[180:181], v[194:195], 2, s[44:45]
	global_load_dwordx4 v[186:189], v[180:181], off nt
	global_load_dwordx4 v[190:193], v[180:181], off offset:16 nt
	v_lshlrev_b64 v[194:195], 1, v[194:195]
	v_cvt_pk_bf16_f32 v110, v110, v111
	v_cvt_pk_bf16_f32 v111, v112, v113
	v_cvt_pk_bf16_f32 v112, v106, v107
	v_cvt_pk_bf16_f32 v113, v108, v109
	v_lshl_add_u64 v[106:107], s[90:91], 0, v[194:195]
	global_store_dwordx4 v[106:107], v[110:113], off
	v_lshlrev_b32_e32 v108, 16, v112
	v_and_b32_e32 v109, 0xffff0000, v112
	v_lshlrev_b32_e32 v106, 16, v113
	v_and_b32_e32 v107, 0xffff0000, v113
	v_lshlrev_b32_e32 v112, 16, v110
	v_and_b32_e32 v113, 0xffff0000, v110
	v_lshlrev_b32_e32 v110, 16, v111
	v_and_b32_e32 v111, 0xffff0000, v111
	s_mov_b64 s[4:5], 0x48000
	s_waitcnt vmcnt(2)
	v_pk_add_f32 v[110:111], v[188:189], v[110:111]
	s_waitcnt vmcnt(1)
	v_pk_add_f32 v[106:107], v[192:193], v[106:107]
	v_pk_add_f32 v[112:113], v[186:187], v[112:113]
	v_pk_add_f32 v[108:109], v[190:191], v[108:109]
	v_pk_mul_f32 v[188:189], v[198:199], v[110:111]
	v_pk_mul_f32 v[186:187], v[200:201], v[112:113]
	v_pk_mul_f32 v[190:191], v[202:203], v[106:107]
	v_pk_mul_f32 v[192:193], v[204:205], v[108:109]
	v_cvt_pk_bf16_f32 v186, v186, v187
	v_cvt_pk_bf16_f32 v187, v188, v189
	s_nop 0
	v_cvt_pk_bf16_f32 v188, v192, v193
	v_cvt_pk_bf16_f32 v189, v190, v191
	v_lshl_add_u64 v[190:191], s[96:97], 0, v[194:195]
	global_store_dwordx4 v[190:191], v[186:189], off
	s_nop 1
	v_lshl_add_u64 v[188:189], v[184:185], 0, s[4:5]
	v_lshl_add_u64 v[212:213], v[188:189], 0, v[148:149]
	v_lshl_add_u64 v[186:187], v[212:213], 2, s[44:45]
	global_load_dwordx4 v[190:193], v[186:187], off nt
	global_load_dwordx4 v[194:197], v[186:187], off offset:16 nt
	v_lshlrev_b64 v[212:213], 1, v[212:213]
	v_cvt_pk_bf16_f32 v94, v94, v95
	v_cvt_pk_bf16_f32 v95, v96, v97
	v_cvt_pk_bf16_f32 v96, v90, v91
	v_cvt_pk_bf16_f32 v97, v92, v93
	v_lshl_add_u64 v[90:91], s[90:91], 0, v[212:213]
	global_store_dwordx4 v[90:91], v[94:97], off
	v_lshlrev_b32_e32 v92, 16, v96
	v_and_b32_e32 v93, 0xffff0000, v96
	v_lshlrev_b32_e32 v90, 16, v97
	v_and_b32_e32 v91, 0xffff0000, v97
	v_lshlrev_b32_e32 v96, 16, v94
	v_and_b32_e32 v97, 0xffff0000, v94
	v_lshlrev_b32_e32 v94, 16, v95
	v_and_b32_e32 v95, 0xffff0000, v95
	s_mov_b64 s[4:5], 0x50000
	s_waitcnt vmcnt(2)
	v_pk_add_f32 v[94:95], v[192:193], v[94:95]
	s_waitcnt vmcnt(1)
	v_pk_add_f32 v[90:91], v[196:197], v[90:91]
	v_pk_add_f32 v[96:97], v[190:191], v[96:97]
	v_pk_add_f32 v[92:93], v[194:195], v[92:93]
	v_pk_mul_f32 v[192:193], v[198:199], v[94:95]
	v_pk_mul_f32 v[190:191], v[200:201], v[96:97]
	v_pk_mul_f32 v[194:195], v[202:203], v[90:91]
	v_pk_mul_f32 v[196:197], v[204:205], v[92:93]
	v_cvt_pk_bf16_f32 v190, v190, v191
	v_cvt_pk_bf16_f32 v191, v192, v193
	s_nop 0
	v_cvt_pk_bf16_f32 v192, v196, v197
	v_cvt_pk_bf16_f32 v193, v194, v195
	v_lshl_add_u64 v[194:195], s[96:97], 0, v[212:213]
	global_store_dwordx4 v[194:195], v[190:193], off
	s_nop 1
	v_lshl_add_u64 v[192:193], v[184:185], 0, s[4:5]
	v_lshl_add_u64 v[220:221], v[192:193], 0, v[148:149]
	v_lshl_add_u64 v[190:191], v[220:221], 2, s[44:45]
	global_load_dwordx4 v[194:197], v[190:191], off nt
	global_load_dwordx4 v[212:215], v[190:191], off offset:16 nt
	v_lshlrev_b64 v[220:221], 1, v[220:221]
	v_cvt_pk_bf16_f32 v86, v86, v87
	v_cvt_pk_bf16_f32 v87, v88, v89
	v_cvt_pk_bf16_f32 v88, v82, v83
	v_cvt_pk_bf16_f32 v89, v84, v85
	v_lshl_add_u64 v[82:83], s[90:91], 0, v[220:221]
	global_store_dwordx4 v[82:83], v[86:89], off
	v_lshlrev_b32_e32 v84, 16, v88
	v_and_b32_e32 v85, 0xffff0000, v88
	v_lshlrev_b32_e32 v82, 16, v89
	v_and_b32_e32 v83, 0xffff0000, v89
	v_lshlrev_b32_e32 v88, 16, v86
	v_and_b32_e32 v89, 0xffff0000, v86
	v_lshlrev_b32_e32 v86, 16, v87
	v_and_b32_e32 v87, 0xffff0000, v87
	s_mov_b64 s[4:5], 0x58000
	s_waitcnt vmcnt(2)
	v_pk_add_f32 v[86:87], v[196:197], v[86:87]
	s_waitcnt vmcnt(1)
	v_pk_add_f32 v[82:83], v[214:215], v[82:83]
	v_pk_add_f32 v[88:89], v[194:195], v[88:89]
	v_pk_add_f32 v[84:85], v[212:213], v[84:85]
	v_pk_mul_f32 v[196:197], v[198:199], v[86:87]
	v_pk_mul_f32 v[194:195], v[200:201], v[88:89]
	v_pk_mul_f32 v[212:213], v[202:203], v[82:83]
	v_pk_mul_f32 v[214:215], v[204:205], v[84:85]
	v_cvt_pk_bf16_f32 v194, v194, v195
	v_cvt_pk_bf16_f32 v195, v196, v197
	s_nop 0
	v_cvt_pk_bf16_f32 v196, v214, v215
	v_cvt_pk_bf16_f32 v197, v212, v213
	v_lshl_add_u64 v[212:213], s[96:97], 0, v[220:221]
	global_store_dwordx4 v[212:213], v[194:197], off
	s_nop 1
	v_lshl_add_u64 v[196:197], v[184:185], 0, s[4:5]
	v_lshl_add_u64 v[224:225], v[196:197], 0, v[148:149]
	v_lshl_add_u64 v[194:195], v[224:225], 2, s[44:45]
	global_load_dwordx4 v[212:215], v[194:195], off nt
	global_load_dwordx4 v[220:223], v[194:195], off offset:16 nt
	v_lshlrev_b64 v[102:103], 1, v[224:225]
	v_cvt_pk_bf16_f32 v78, v78, v79
	v_cvt_pk_bf16_f32 v79, v80, v81
	v_cvt_pk_bf16_f32 v80, v74, v75
	v_cvt_pk_bf16_f32 v81, v76, v77
	v_lshl_add_u64 v[74:75], s[90:91], 0, v[102:103]
	global_store_dwordx4 v[74:75], v[78:81], off
	v_lshlrev_b32_e32 v76, 16, v80
	v_and_b32_e32 v77, 0xffff0000, v80
	v_lshlrev_b32_e32 v74, 16, v81
	v_and_b32_e32 v75, 0xffff0000, v81
	v_lshlrev_b32_e32 v80, 16, v78
	v_and_b32_e32 v81, 0xffff0000, v78
	v_lshlrev_b32_e32 v78, 16, v79
	v_and_b32_e32 v79, 0xffff0000, v79
	v_lshl_add_u64 v[102:103], s[96:97], 0, v[102:103]
	v_or_b32_e32 v148, 0x80, v148
	s_waitcnt vmcnt(2)
; __device__ __forceinline__ unsigned cvt_pk_bf16(float lo, float hi) { unsigned r; asm volatile("v_cvt_pk_bf16_f32 %0, %1, %2" : "=v"(r) : "v"(lo), "v"(hi)); return r; }
;     __device__ __forceinline__ void operator()(const f32x4 (&acc)[2][2][4][2], const Unit& u, int wr, int wc, int fr, int fq) const {
;     ...
;                 for (int m = 0; m < 4; ++m) { const size_t off = (size_t)(row0 + ai * HALF + m * 16) * 2048 + col0 + bj * HALF;
;                     f32x4 x0 = __builtin_nontemporal_load((const f32x4*)(base + off)), x1 = __builtin_nontemporal_load((const f32x4*)(base + off + 4));
;                     if constexpr (HAS_DIN) { const u32x4 dw = __builtin_nontemporal_load((const u32x4*)(dbuf + off));
;                         x0 += (f32x4){__builtin_bit_cast(float, dw.x << 16), __builtin_bit_cast(float, dw.x & 0xffff0000u), __builtin_bit_cast(float, dw.y << 16), __builtin_bit_cast(float, dw.y & 0xffff0000u)};
;                         x1 += (f32x4){__builtin_bit_cast(float, dw.z << 16), __builtin_bit_cast(float, dw.z & 0xffff0000u), __builtin_bit_cast(float, dw.w << 16), __builtin_bit_cast(float, dw.w & 0xffff0000u)}; }
;                     f32x4 o0, o1;
;                     if constexpr (OUT_DELTA) { const f32x4 d0 = g0 * acc[ai][bj][m][0], d1 = g1 * acc[ai][bj][m][1];
;                         u32x4 w; w.x = cvt_pk_bf16(d0[0], d0[1]); w.y = cvt_pk_bf16(d0[2], d0[3]); w.z = cvt_pk_bf16(d1[0], d1[1]); w.w = cvt_pk_bf16(d1[2], d1[3]);
;                         *(u32x4*)(dbuf + off) = w;
;                         o0 = x0 + (f32x4){__builtin_bit_cast(float, w.x << 16), __builtin_bit_cast(float, w.x & 0xffff0000u), __builtin_bit_cast(float, w.y << 16), __builtin_bit_cast(float, w.y & 0xffff0000u)};
;                         o1 = x1 + (f32x4){__builtin_bit_cast(float, w.z << 16), __builtin_bit_cast(float, w.z & 0xffff0000u), __builtin_bit_cast(float, w.w << 16), __builtin_bit_cast(float, w.w & 0xffff0000u)}; }
;                     else { o0 = x0 + g0 * acc[ai][bj][m][0]; o1 = x1 + g1 * acc[ai][bj][m][1]; *(f32x4*)(out + off) = o0; *(f32x4*)(out + off + 4) = o1; }
;                     if (Hn) { const f32x4 h0 = o0 * G0, h1 = o1 * G1;
;                         u32x4 w; w.x = cvt_pk_bf16(h0[0], h0[1]); w.y = cvt_pk_bf16(h0[2], h0[3]); w.z = cvt_pk_bf16(h1[0], h1[1]); w.w = cvt_pk_bf16(h1[2], h1[3]);
;                         *(u32x4*)(Hn + off) = w;
	v_pk_add_f32 v[78:79], v[214:215], v[78:79]
	v_pk_add_f32 v[80:81], v[212:213], v[80:81]
	s_waitcnt vmcnt(1)
	v_pk_add_f32 v[74:75], v[222:223], v[74:75]
	v_pk_add_f32 v[76:77], v[220:221], v[76:77]
	v_pk_mul_f32 v[100:101], v[198:199], v[78:79]
	v_pk_mul_f32 v[98:99], v[200:201], v[80:81]
	v_pk_mul_f32 v[104:105], v[202:203], v[74:75]
	v_pk_mul_f32 v[198:199], v[204:205], v[76:77]
	v_cvt_pk_bf16_f32 v98, v98, v99
	v_cvt_pk_bf16_f32 v99, v100, v101
	s_nop 0
	v_cvt_pk_bf16_f32 v100, v198, v199
	v_cvt_pk_bf16_f32 v101, v104, v105
	global_store_dwordx4 v[102:103], v[98:101], off
	global_load_dwordx4 v[100:103], v[178:179], off offset:512 nt
	global_load_dwordx4 v[198:201], v[178:179], off offset:528 nt
	v_lshl_add_u64 v[98:99], v[184:185], 0, v[148:149]
	v_pk_mul_f32 v[104:105], v[68:69], v[28:29]
	v_pk_mul_f32 v[68:69], v[66:67], v[26:27]
	v_cvt_pk_bf16_f32 v66, v70, v71
	v_cvt_pk_bf16_f32 v67, v72, v73
	s_nop 0
	v_cvt_pk_bf16_f32 v68, v68, v69
	v_cvt_pk_bf16_f32 v69, v104, v105
	v_lshlrev_b64 v[104:105], 1, v[98:99]
	v_lshl_add_u64 v[70:71], s[90:91], 0, v[104:105]
	global_store_dwordx4 v[70:71], v[66:69], off
	v_lshlrev_b32_e32 v72, 16, v68
	v_and_b32_e32 v73, 0xffff0000, v68
	v_lshlrev_b32_e32 v68, 16, v69
	v_and_b32_e32 v69, 0xffff0000, v69
	s_waitcnt vmcnt(1)
	v_pk_add_f32 v[70:71], v[200:201], v[68:69]
	v_lshlrev_b32_e32 v68, 16, v66
	v_and_b32_e32 v69, 0xffff0000, v66
	v_lshlrev_b32_e32 v66, 16, v67
	v_and_b32_e32 v67, 0xffff0000, v67
	v_pk_add_f32 v[98:99], v[102:103], v[66:67]
	v_pk_add_f32 v[100:101], v[100:101], v[68:69]
	v_pk_add_f32 v[72:73], v[198:199], v[72:73]
	v_pk_mul_f32 v[68:69], v[150:151], v[98:99]
	v_pk_mul_f32 v[66:67], v[152:153], v[100:101]
	v_pk_mul_f32 v[102:103], v[154:155], v[70:71]
	v_pk_mul_f32 v[178:179], v[156:157], v[72:73]
	v_cvt_pk_bf16_f32 v66, v66, v67
	v_cvt_pk_bf16_f32 v67, v68, v69
	s_nop 0
	v_cvt_pk_bf16_f32 v68, v178, v179
	v_cvt_pk_bf16_f32 v69, v102, v103
	v_lshl_add_u64 v[102:103], s[96:97], 0, v[104:105]
	global_store_dwordx4 v[102:103], v[66:69], off
	s_nop 1
	v_mul_f32_e32 v66, v101, v101
	v_mul_f32_e32 v67, v99, v99
	v_fmac_f32_e32 v66, v100, v100
	v_fmac_f32_e32 v67, v98, v98
	v_add_f32_e32 v66, v66, v67
	v_mul_f32_e32 v67, v73, v73
	v_mul_f32_e32 v68, v71, v71
	v_fmac_f32_e32 v67, v72, v72
	v_fmac_f32_e32 v68, v70, v70
	v_add_f32_e32 v67, v67, v68
	global_load_dwordx4 v[68:71], v[138:139], off offset:512 nt
	global_load_dwordx4 v[98:101], v[138:139], off offset:528 nt
	v_lshl_add_u64 v[72:73], v[140:141], 0, v[148:149]
	v_lshlrev_b64 v[72:73], 1, v[72:73]
	v_cvt_pk_bf16_f32 v62, v62, v63
	v_cvt_pk_bf16_f32 v63, v64, v65
	v_cvt_pk_bf16_f32 v64, v58, v59
	v_cvt_pk_bf16_f32 v65, v60, v61
	v_lshl_add_u64 v[58:59], s[90:91], 0, v[72:73]
	global_store_dwordx4 v[58:59], v[62:65], off
	v_lshlrev_b32_e32 v60, 16, v64
	v_and_b32_e32 v61, 0xffff0000, v64
	v_lshlrev_b32_e32 v58, 16, v65
	v_and_b32_e32 v59, 0xffff0000, v65
	v_lshlrev_b32_e32 v64, 16, v62
	v_and_b32_e32 v65, 0xffff0000, v62
	v_lshlrev_b32_e32 v62, 16, v63
	v_and_b32_e32 v63, 0xffff0000, v63
	v_lshl_add_u64 v[72:73], s[96:97], 0, v[72:73]
	v_add_f32_e32 v66, v66, v67
	v_add_f32_e32 v66, v211, v66
	s_waitcnt vmcnt(2)
	v_pk_add_f32 v[62:63], v[70:71], v[62:63]
	v_pk_add_f32 v[64:65], v[68:69], v[64:65]
	s_waitcnt vmcnt(1)
	v_pk_add_f32 v[58:59], v[100:101], v[58:59]
	v_pk_add_f32 v[60:61], v[98:99], v[60:61]
	v_pk_mul_f32 v[70:71], v[150:151], v[62:63]
	v_pk_mul_f32 v[68:69], v[152:153], v[64:65]
	v_pk_mul_f32 v[98:99], v[154:155], v[58:59]
	v_pk_mul_f32 v[100:101], v[156:157], v[60:61]
	v_cvt_pk_bf16_f32 v68, v68, v69
	v_cvt_pk_bf16_f32 v69, v70, v71
	s_nop 0
	v_cvt_pk_bf16_f32 v70, v100, v101
	v_cvt_pk_bf16_f32 v71, v98, v99
	global_store_dwordx4 v[72:73], v[68:71], off
	global_load_dwordx4 v[68:71], v[142:143], off offset:512 nt
	s_nop 0
	global_load_dwordx4 v[98:101], v[142:143], off offset:528 nt
	v_lshl_add_u64 v[72:73], v[144:145], 0, v[148:149]
	v_lshlrev_b64 v[72:73], 1, v[72:73]
	v_cvt_pk_bf16_f32 v54, v54, v55
	v_cvt_pk_bf16_f32 v55, v56, v57
	v_cvt_pk_bf16_f32 v56, v50, v51
	v_cvt_pk_bf16_f32 v57, v52, v53
	v_lshl_add_u64 v[50:51], s[90:91], 0, v[72:73]
	global_store_dwordx4 v[50:51], v[54:57], off
	v_lshlrev_b32_e32 v52, 16, v56
	v_and_b32_e32 v53, 0xffff0000, v56
	v_lshlrev_b32_e32 v50, 16, v57
	v_and_b32_e32 v51, 0xffff0000, v57
	v_lshlrev_b32_e32 v56, 16, v54
	v_and_b32_e32 v57, 0xffff0000, v54
	v_lshlrev_b32_e32 v54, 16, v55
	v_and_b32_e32 v55, 0xffff0000, v55
	v_lshl_add_u64 v[72:73], s[96:97], 0, v[72:73]
	s_waitcnt vmcnt(2)
	v_pk_add_f32 v[54:55], v[70:71], v[54:55]
	v_pk_add_f32 v[56:57], v[68:69], v[56:57]
	s_waitcnt vmcnt(1)
	v_pk_add_f32 v[50:51], v[100:101], v[50:51]
	v_pk_add_f32 v[52:53], v[98:99], v[52:53]
	v_pk_mul_f32 v[70:71], v[150:151], v[54:55]
	v_pk_mul_f32 v[68:69], v[152:153], v[56:57]
	v_pk_mul_f32 v[98:99], v[154:155], v[50:51]
	v_pk_mul_f32 v[100:101], v[156:157], v[52:53]
	v_cvt_pk_bf16_f32 v68, v68, v69
	v_cvt_pk_bf16_f32 v69, v70, v71
	s_nop 0
	v_cvt_pk_bf16_f32 v70, v100, v101
	v_cvt_pk_bf16_f32 v71, v98, v99
	global_store_dwordx4 v[72:73], v[68:71], off
	global_load_dwordx4 v[68:71], v[158:159], off offset:512 nt
	s_nop 0
	global_load_dwordx4 v[98:101], v[158:159], off offset:528 nt
	v_lshl_add_u64 v[72:73], v[160:161], 0, v[148:149]
	v_lshlrev_b64 v[72:73], 1, v[72:73]
	v_cvt_pk_bf16_f32 v46, v46, v47
	v_cvt_pk_bf16_f32 v47, v48, v49
	v_cvt_pk_bf16_f32 v48, v42, v43
	v_cvt_pk_bf16_f32 v49, v44, v45
	v_lshl_add_u64 v[42:43], s[90:91], 0, v[72:73]
	global_store_dwordx4 v[42:43], v[46:49], off
	v_lshlrev_b32_e32 v44, 16, v48
	v_and_b32_e32 v45, 0xffff0000, v48
	v_lshlrev_b32_e32 v42, 16, v49
	v_and_b32_e32 v43, 0xffff0000, v49
	v_lshlrev_b32_e32 v48, 16, v46
	v_and_b32_e32 v49, 0xffff0000, v46
	v_lshlrev_b32_e32 v46, 16, v47
	v_and_b32_e32 v47, 0xffff0000, v47
	v_lshl_add_u64 v[72:73], s[96:97], 0, v[72:73]
	s_waitcnt vmcnt(2)
; __device__ __forceinline__ unsigned cvt_pk_bf16(float lo, float hi) { unsigned r; asm volatile("v_cvt_pk_bf16_f32 %0, %1, %2" : "=v"(r) : "v"(lo), "v"(hi)); return r; }
;     __device__ __forceinline__ void operator()(const f32x4 (&acc)[2][2][4][2], const Unit& u, int wr, int wc, int fr, int fq) const {
;     ...
;                 for (int m = 0; m < 4; ++m) { const size_t off = (size_t)(row0 + ai * HALF + m * 16) * 2048 + col0 + bj * HALF;
;                     f32x4 x0 = __builtin_nontemporal_load((const f32x4*)(base + off)), x1 = __builtin_nontemporal_load((const f32x4*)(base + off + 4));
;                     if constexpr (HAS_DIN) { const u32x4 dw = __builtin_nontemporal_load((const u32x4*)(dbuf + off));
;                         x0 += (f32x4){__builtin_bit_cast(float, dw.x << 16), __builtin_bit_cast(float, dw.x & 0xffff0000u), __builtin_bit_cast(float, dw.y << 16), __builtin_bit_cast(float, dw.y & 0xffff0000u)};
;                         x1 += (f32x4){__builtin_bit_cast(float, dw.z << 16), __builtin_bit_cast(float, dw.z & 0xffff0000u), __builtin_bit_cast(float, dw.w << 16), __builtin_bit_cast(float, dw.w & 0xffff0000u)}; }
;                     f32x4 o0, o1;
;                     if constexpr (OUT_DELTA) { const f32x4 d0 = g0 * acc[ai][bj][m][0], d1 = g1 * acc[ai][bj][m][1];
;                         u32x4 w; w.x = cvt_pk_bf16(d0[0], d0[1]); w.y = cvt_pk_bf16(d0[2], d0[3]); w.z = cvt_pk_bf16(d1[0], d1[1]); w.w = cvt_pk_bf16(d1[2], d1[3]);
;                         *(u32x4*)(dbuf + off) = w;
;                         o0 = x0 + (f32x4){__builtin_bit_cast(float, w.x << 16), __builtin_bit_cast(float, w.x & 0xffff0000u), __builtin_bit_cast(float, w.y << 16), __builtin_bit_cast(float, w.y & 0xffff0000u)};
;                         o1 = x1 + (f32x4){__builtin_bit_cast(float, w.z << 16), __builtin_bit_cast(float, w.z & 0xffff0000u), __builtin_bit_cast(float, w.w << 16), __builtin_bit_cast(float, w.w & 0xffff0000u)}; }
;                     else { o0 = x0 + g0 * acc[ai][bj][m][0]; o1 = x1 + g1 * acc[ai][bj][m][1]; *(f32x4*)(out + off) = o0; *(f32x4*)(out + off + 4) = o1; }
;                     if (Hn) { const f32x4 h0 = o0 * G0, h1 = o1 * G1;
;                         u32x4 w; w.x = cvt_pk_bf16(h0[0], h0[1]); w.y = cvt_pk_bf16(h0[2], h0[3]); w.z = cvt_pk_bf16(h1[0], h1[1]); w.w = cvt_pk_bf16(h1[2], h1[3]);
;                         *(u32x4*)(Hn + off) = w;
	v_pk_add_f32 v[46:47], v[70:71], v[46:47]
	v_pk_add_f32 v[48:49], v[68:69], v[48:49]
	s_waitcnt vmcnt(1)
	v_pk_add_f32 v[42:43], v[100:101], v[42:43]
	v_pk_add_f32 v[44:45], v[98:99], v[44:45]
	v_pk_mul_f32 v[70:71], v[150:151], v[46:47]
	v_pk_mul_f32 v[68:69], v[152:153], v[48:49]
	v_pk_mul_f32 v[98:99], v[154:155], v[42:43]
	v_pk_mul_f32 v[100:101], v[156:157], v[44:45]
	v_cvt_pk_bf16_f32 v68, v68, v69
	v_cvt_pk_bf16_f32 v69, v70, v71
	s_nop 0
	v_cvt_pk_bf16_f32 v70, v100, v101
	v_cvt_pk_bf16_f32 v71, v98, v99
	global_store_dwordx4 v[72:73], v[68:71], off
	global_load_dwordx4 v[68:71], v[180:181], off offset:512 nt
	s_nop 0
	global_load_dwordx4 v[98:101], v[180:181], off offset:528 nt
	v_lshl_add_u64 v[72:73], v[182:183], 0, v[148:149]
	v_lshlrev_b64 v[72:73], 1, v[72:73]
	v_cvt_pk_bf16_f32 v38, v38, v39
	v_cvt_pk_bf16_f32 v39, v40, v41
	v_cvt_pk_bf16_f32 v40, v34, v35
	v_cvt_pk_bf16_f32 v41, v36, v37
	v_lshl_add_u64 v[34:35], s[90:91], 0, v[72:73]
	global_store_dwordx4 v[34:35], v[38:41], off
	v_lshlrev_b32_e32 v36, 16, v40
	v_and_b32_e32 v37, 0xffff0000, v40
	v_lshlrev_b32_e32 v34, 16, v41
	v_and_b32_e32 v35, 0xffff0000, v41
	v_lshlrev_b32_e32 v40, 16, v38
	v_and_b32_e32 v41, 0xffff0000, v38
	v_lshlrev_b32_e32 v38, 16, v39
	v_and_b32_e32 v39, 0xffff0000, v39
	v_lshl_add_u64 v[72:73], s[96:97], 0, v[72:73]
	s_waitcnt vmcnt(2)
	v_pk_add_f32 v[38:39], v[70:71], v[38:39]
	v_pk_add_f32 v[40:41], v[68:69], v[40:41]
	s_waitcnt vmcnt(1)
	v_pk_add_f32 v[34:35], v[100:101], v[34:35]
	v_pk_add_f32 v[36:37], v[98:99], v[36:37]
	v_pk_mul_f32 v[70:71], v[150:151], v[38:39]
	v_pk_mul_f32 v[68:69], v[152:153], v[40:41]
	v_pk_mul_f32 v[98:99], v[154:155], v[34:35]
	v_pk_mul_f32 v[100:101], v[156:157], v[36:37]
	v_cvt_pk_bf16_f32 v68, v68, v69
	v_cvt_pk_bf16_f32 v69, v70, v71
	s_nop 0
	v_cvt_pk_bf16_f32 v70, v100, v101
	v_cvt_pk_bf16_f32 v71, v98, v99
	global_store_dwordx4 v[72:73], v[68:71], off
	global_load_dwordx4 v[68:71], v[186:187], off offset:512 nt
	s_nop 0
	global_load_dwordx4 v[98:101], v[186:187], off offset:528 nt
	v_lshl_add_u64 v[72:73], v[188:189], 0, v[148:149]
	v_lshlrev_b64 v[72:73], 1, v[72:73]
	v_cvt_pk_bf16_f32 v22, v22, v23
	v_cvt_pk_bf16_f32 v23, v24, v25
	v_cvt_pk_bf16_f32 v24, v18, v19
	v_cvt_pk_bf16_f32 v25, v20, v21
	v_lshl_add_u64 v[18:19], s[90:91], 0, v[72:73]
	global_store_dwordx4 v[18:19], v[22:25], off
	v_lshlrev_b32_e32 v20, 16, v24
	v_and_b32_e32 v21, 0xffff0000, v24
	v_lshlrev_b32_e32 v18, 16, v25
	v_and_b32_e32 v19, 0xffff0000, v25
	v_lshlrev_b32_e32 v24, 16, v22
	v_and_b32_e32 v25, 0xffff0000, v22
	v_lshlrev_b32_e32 v22, 16, v23
	v_and_b32_e32 v23, 0xffff0000, v23
	v_lshl_add_u64 v[72:73], s[96:97], 0, v[72:73]
	s_waitcnt vmcnt(2)
	v_pk_add_f32 v[22:23], v[70:71], v[22:23]
	v_pk_add_f32 v[24:25], v[68:69], v[24:25]
	s_waitcnt vmcnt(1)
	v_pk_add_f32 v[18:19], v[100:101], v[18:19]
	v_pk_add_f32 v[20:21], v[98:99], v[20:21]
	v_pk_mul_f32 v[70:71], v[150:151], v[22:23]
	v_pk_mul_f32 v[68:69], v[152:153], v[24:25]
	v_pk_mul_f32 v[98:99], v[154:155], v[18:19]
	v_pk_mul_f32 v[100:101], v[156:157], v[20:21]
	v_cvt_pk_bf16_f32 v68, v68, v69
	v_cvt_pk_bf16_f32 v69, v70, v71
	s_nop 0
	v_cvt_pk_bf16_f32 v70, v100, v101
	v_cvt_pk_bf16_f32 v71, v98, v99
	global_store_dwordx4 v[72:73], v[68:71], off
	global_load_dwordx4 v[68:71], v[190:191], off offset:512 nt
	s_nop 0
	global_load_dwordx4 v[98:101], v[190:191], off offset:528 nt
	v_lshl_add_u64 v[72:73], v[192:193], 0, v[148:149]
	v_lshlrev_b64 v[72:73], 1, v[72:73]
	v_cvt_pk_bf16_f32 v14, v14, v15
	v_cvt_pk_bf16_f32 v15, v16, v17
	v_cvt_pk_bf16_f32 v16, v10, v11
	v_cvt_pk_bf16_f32 v17, v12, v13
	v_lshl_add_u64 v[10:11], s[90:91], 0, v[72:73]
	global_store_dwordx4 v[10:11], v[14:17], off
	v_lshlrev_b32_e32 v12, 16, v16
	v_and_b32_e32 v13, 0xffff0000, v16
	v_lshlrev_b32_e32 v10, 16, v17
	v_and_b32_e32 v11, 0xffff0000, v17
	v_lshlrev_b32_e32 v16, 16, v14
	v_and_b32_e32 v17, 0xffff0000, v14
	v_lshlrev_b32_e32 v14, 16, v15
	v_and_b32_e32 v15, 0xffff0000, v15
	v_lshl_add_u64 v[72:73], s[96:97], 0, v[72:73]
	s_waitcnt vmcnt(2)
	v_pk_add_f32 v[14:15], v[70:71], v[14:15]
	v_pk_add_f32 v[16:17], v[68:69], v[16:17]
	s_waitcnt vmcnt(1)
	v_pk_add_f32 v[10:11], v[100:101], v[10:11]
	v_pk_add_f32 v[12:13], v[98:99], v[12:13]
	v_pk_mul_f32 v[70:71], v[150:151], v[14:15]
	v_pk_mul_f32 v[68:69], v[152:153], v[16:17]
	v_pk_mul_f32 v[98:99], v[154:155], v[10:11]
	v_pk_mul_f32 v[100:101], v[156:157], v[12:13]
	v_cvt_pk_bf16_f32 v68, v68, v69
	v_cvt_pk_bf16_f32 v69, v70, v71
	s_nop 0
	v_cvt_pk_bf16_f32 v70, v100, v101
	v_cvt_pk_bf16_f32 v71, v98, v99
	global_store_dwordx4 v[72:73], v[68:71], off
	global_load_dwordx4 v[68:71], v[194:195], off offset:512 nt
	s_nop 0
	global_load_dwordx4 v[98:101], v[194:195], off offset:528 nt
	v_lshl_add_u64 v[72:73], v[196:197], 0, v[148:149]
	v_lshlrev_b64 v[30:31], 1, v[72:73]
	v_cvt_pk_bf16_f32 v6, v6, v7
	v_cvt_pk_bf16_f32 v7, v8, v9
	v_cvt_pk_bf16_f32 v8, v2, v3
	v_cvt_pk_bf16_f32 v9, v4, v5
	v_lshl_add_u64 v[2:3], s[90:91], 0, v[30:31]
	global_store_dwordx4 v[2:3], v[6:9], off
	v_lshlrev_b32_e32 v4, 16, v8
	v_and_b32_e32 v5, 0xffff0000, v8
	v_lshlrev_b32_e32 v2, 16, v9
	v_and_b32_e32 v3, 0xffff0000, v9
	v_lshlrev_b32_e32 v8, 16, v6
	v_and_b32_e32 v9, 0xffff0000, v6
	v_lshlrev_b32_e32 v6, 16, v7
	v_and_b32_e32 v7, 0xffff0000, v7
	v_lshl_add_u64 v[30:31], s[96:97], 0, v[30:31]
	s_waitcnt vmcnt(2)
	v_pk_add_f32 v[8:9], v[68:69], v[8:9]
	v_pk_add_f32 v[6:7], v[70:71], v[6:7]
	v_pk_mul_f32 v[26:27], v[152:153], v[8:9]
	s_waitcnt vmcnt(1)
	v_pk_add_f32 v[2:3], v[100:101], v[2:3]
	v_pk_add_f32 v[4:5], v[98:99], v[4:5]
	v_pk_mul_f32 v[28:29], v[150:151], v[6:7]
	v_cvt_pk_bf16_f32 v26, v26, v27
	v_pk_mul_f32 v[32:33], v[154:155], v[2:3]
	v_cvt_pk_bf16_f32 v27, v28, v29
	v_pk_mul_f32 v[68:69], v[156:157], v[4:5]
	s_nop 0
	v_cvt_pk_bf16_f32 v28, v68, v69
	v_cvt_pk_bf16_f32 v29, v32, v33
	global_store_dwordx4 v[30:31], v[26:29], off
	s_nop 1
	v_and_b32_e32 v27, 64, v218
	v_xor_b32_e32 v26, 16, v218
	v_add_u32_e32 v27, 64, v27
	v_cmp_lt_i32_e32 vcc, v26, v27
	s_nop 1
	v_cndmask_b32_e32 v26, v218, v26, vcc
	v_lshlrev_b32_e32 v28, 2, v26
	v_xor_b32_e32 v26, 32, v218
	v_cmp_lt_i32_e32 vcc, v26, v27
	s_nop 1
	v_cndmask_b32_e32 v26, v218, v26, vcc
	v_lshlrev_b32_e32 v29, 2, v26
	ds_bpermute_b32 v26, v28, v66
	s_waitcnt lgkmcnt(0)
	v_add_f32_e32 v30, v66, v26
	ds_bpermute_b32 v31, v29, v30
	v_lshl_add_u64 v[26:27], v[146:147], 3, s[42:43]
	s_and_saveexec_b64 s[4:5], s[0:1]
	s_mov_b32 s8, 0x2f800000
	s_mov_b32 s9, 0xcf800000
	s_cbranch_execz .LBB0_558
	s_waitcnt lgkmcnt(0)
	v_add_f32_e32 v30, v30, v31
	v_mul_f32_e32 v30, 0x47800000, v30
	v_rndne_f32_e32 v30, v30
	v_mul_f32_e64 v31, |v30|, s8
	v_floor_f32_e32 v31, v31
	v_fma_f32 v32, v31, s9, |v30|
	v_cvt_u32_f32_e32 v32, v32
	v_cvt_u32_f32_e32 v31, v31
	v_ashrrev_i32_e32 v33, 31, v30
	v_xor_b32_e32 v30, v32, v33
	v_xor_b32_e32 v31, v31, v33
	v_sub_co_u32_e32 v30, vcc, v30, v33
	s_nop 1
	v_subb_co_u32_e32 v31, vcc, v31, v33, vcc
	global_atomic_add_x2 v[26:27], v[30:31], off

; #define PG8_STAGE(bufoff, gbase, voff) do { const char* gb_ = (const char*)(gbase); asm volatile("" : "+s"(gb_)); _Pragma("unroll") for (int _i = 0; _i < 2; ++_i) { unsigned vo_ = (voff)[_i]; asm volatile("" : "+v"(vo_));        \
;         __builtin_amdgcn_global_load_lds((const unsigned*)(gb_ + vo_), (PG8_LAS unsigned*)(lds + (bufoff) + ldsw + _i * 8192), 16, 0, 0); } } while (0)
; #define PG8_LDA(dst, b, h) do { _Pragma("unroll") for (int m = 0; m < 4; ++m) _Pragma("unroll") for (int k = 0; k < 2; ++k) dst[m][k] = *(const PG8_LAS bf16x8*)(lds + PG8_SA(b, h) + aoff + m * 2048 + k * 1024); } while (0)
; #define PG8_LDB(dst, b, h) do { _Pragma("unroll") for (int n = 0; n < 2; ++n) _Pragma("unroll") for (int k = 0; k < 2; ++k) dst[n][k] = *(const PG8_LAS bf16x8*)(lds + PG8_SB(b, h) + boff + n * 2048 + k * 1024); } while (0)
; #define PG8_WAIT_V(n) asm volatile("s_waitcnt vmcnt(" #n ")" ::: "memory")
; #define PG8_WAIT_L(n) asm volatile("s_waitcnt lgkmcnt(" #n ")" ::: "memory")
; template <class Epi, class Sched, bool ALIGN_EPI = false, bool SP2 = false>
; __device__ __forceinline__ void gemm_phase(PG8_LAS unsigned char* lds, const Gemm g, const Sched& S, const Epi& E) {
;     ...
;         const bool has_next = S.next(ui + 1, nxt);
;         const char* nA = has_next ? (const char*)g.A + (size_t)nxt.pm * tstep : cA; const char* nB = has_next ? (const char*)g.Bt + (size_t)nxt.pn * tstep : cB;
;         for (int t = 0; t < nt; t += 2) {
;             const bool last = (t == nt - 2);
;             const char* a1 = cA + (size_t)(t + 1) * kstep;
;             const char* a2 = last ? nA : cA + (size_t)(t + 2) * kstep; const char* b2 = last ? nB : cB + (size_t)(t + 2) * kstep;
;             const char* a3 = a2 + kstep; const char* b3 = b2 + kstep;
;             if (last && has_next) S.a_ready(nxt);
;             if constexpr (SP2) {
;             PG8_LDB(B0, 0, 0); PG8_LDB(B1, 0, 1); PG8_SCHED; PG8_LDA(At, 0, 0); PG8_STAGE(PG8_SA(1, 1), a1 + hstep, voffA);
;             PG8_WAIT_V(8); PG8_WAIT_L(0); PG8_BAR; PG8_MMA(0, 0, At, B0); PG8_MMA(0, 1, At, B1); PG8_BAR; PG8_SCHED;
;             PG8_LDA(At, 0, 1); PG8_STAGE(PG8_SB(0, 0), b2, voffB); PG8_STAGE(PG8_SB(0, 1), b2 + hstep, voffB); PG8_STAGE(PG8_SA(0, 0), a2, voffA);
;             PG8_WAIT_V(8); PG8_WAIT_L(0); PG8_BAR; PG8_MMA(1, 0, At, B0); PG8_MMA(1, 1, At, B1); PG8_BAR; PG8_SCHED;
.LBB0_634:
	s_add_u32 s16, s14, 0x100
	s_addc_u32 s17, s15, 0
	s_cmp_eq_u32 s53, 28
	s_cselect_b32 s22, s49, s16
	s_cselect_b32 s23, s7, s17
	s_cselect_b32 s20, s50, s51
	s_cselect_b32 s21, s5, s52
	s_add_u32 s18, s22, 0x80
	s_addc_u32 s19, s23, 0
	s_add_i32 s54, 0, 0x10000
	s_add_i32 s55, 0, 0x14000
	ds_read_b128 v[82:85], v244
	ds_read_b128 v[86:89], v244 offset:1024
	ds_read_b128 v[90:93], v244 offset:2048
	ds_read_b128 v[94:97], v244 offset:3072
	ds_read_b128 v[146:149], v244 offset:16384
	ds_read_b128 v[150:153], v244 offset:17408
	ds_read_b128 v[154:157], v244 offset:18432
	ds_read_b128 v[158:161], v244 offset:19456
	s_add_u32 s14, s14, 0x80080
	s_addc_u32 s15, s15, 0
	ds_read_b128 v[178:181], v188
	ds_read_b128 v[190:193], v188 offset:1024
	ds_read_b128 v[194:197], v188 offset:2048
	ds_read_b128 v[198:201], v188 offset:3072
	ds_read_b128 v[202:205], v188 offset:4096
	ds_read_b128 v[206:209], v188 offset:5120
	ds_read_b128 v[210:213], v188 offset:6144
	ds_read_b128 v[220:223], v188 offset:7168
	s_add_i32 m0, s27, 0xc000
	s_nop 0
	global_load_lds_dwordx4 v1, s[14:15]
	s_add_i32 m0, s27, 0xe000
	s_nop 0
	global_load_lds_dwordx4 v164, s[14:15]
	s_waitcnt vmcnt(8)
	s_waitcnt lgkmcnt(0)
	s_barrier
	s_setprio 0
	s_waitcnt lgkmcnt(0)
	v_mfma_f32_16x16x32_bf16 v[142:145], v[82:85], v[178:181], v[142:145]
	v_mfma_f32_16x16x32_bf16 v[142:145], v[86:89], v[190:193], v[142:145]
	v_mfma_f32_16x16x32_bf16 v[126:129], v[82:85], v[194:197], v[126:129]
	v_mfma_f32_16x16x32_bf16 v[126:129], v[86:89], v[198:201], v[126:129]
	v_mfma_f32_16x16x32_bf16 v[110:113], v[82:85], v[202:205], v[110:113]
	v_mfma_f32_16x16x32_bf16 v[110:113], v[86:89], v[206:209], v[110:113]
	v_mfma_f32_16x16x32_bf16 v[78:81], v[82:85], v[210:213], v[78:81]
	v_mfma_f32_16x16x32_bf16 v[78:81], v[86:89], v[220:223], v[78:81]
	v_mfma_f32_16x16x32_bf16 v[138:141], v[90:93], v[178:181], v[138:141]
	v_mfma_f32_16x16x32_bf16 v[138:141], v[94:97], v[190:193], v[138:141]
	v_mfma_f32_16x16x32_bf16 v[122:125], v[90:93], v[194:197], v[122:125]
	v_mfma_f32_16x16x32_bf16 v[122:125], v[94:97], v[198:201], v[122:125]
	v_mfma_f32_16x16x32_bf16 v[106:109], v[90:93], v[202:205], v[106:109]
	v_mfma_f32_16x16x32_bf16 v[106:109], v[94:97], v[206:209], v[106:109]
	v_mfma_f32_16x16x32_bf16 v[74:77], v[90:93], v[210:213], v[74:77]
	v_mfma_f32_16x16x32_bf16 v[74:77], v[94:97], v[220:223], v[74:77]
	v_mfma_f32_16x16x32_bf16 v[134:137], v[146:149], v[178:181], v[134:137]
	v_mfma_f32_16x16x32_bf16 v[134:137], v[150:153], v[190:193], v[134:137]
	v_mfma_f32_16x16x32_bf16 v[118:121], v[146:149], v[194:197], v[118:121]
	v_mfma_f32_16x16x32_bf16 v[118:121], v[150:153], v[198:201], v[118:121]
	v_mfma_f32_16x16x32_bf16 v[102:105], v[146:149], v[202:205], v[102:105]
	v_mfma_f32_16x16x32_bf16 v[102:105], v[150:153], v[206:209], v[102:105]
	v_mfma_f32_16x16x32_bf16 v[70:73], v[146:149], v[210:213], v[70:73]
	v_mfma_f32_16x16x32_bf16 v[70:73], v[150:153], v[220:223], v[70:73]
	v_mfma_f32_16x16x32_bf16 v[130:133], v[154:157], v[178:181], v[130:133]
	v_mfma_f32_16x16x32_bf16 v[130:133], v[158:161], v[190:193], v[130:133]
	v_mfma_f32_16x16x32_bf16 v[114:117], v[154:157], v[194:197], v[114:117]
	v_mfma_f32_16x16x32_bf16 v[114:117], v[158:161], v[198:201], v[114:117]
	v_mfma_f32_16x16x32_bf16 v[98:101], v[154:157], v[202:205], v[98:101]
	v_mfma_f32_16x16x32_bf16 v[98:101], v[158:161], v[206:209], v[98:101]
	v_mfma_f32_16x16x32_bf16 v[66:69], v[154:157], v[210:213], v[66:69]
	v_mfma_f32_16x16x32_bf16 v[66:69], v[158:161], v[220:223], v[66:69]
	s_setprio 1
	s_barrier
	s_mov_b64 s[14:15], s[20:21]
	s_add_i32 s54, s54, s26
	ds_read_b128 v[178:181], v188 offset:16384
	ds_read_b128 v[190:193], v188 offset:17408
	ds_read_b128 v[194:197], v188 offset:18432
	ds_read_b128 v[198:201], v188 offset:19456
	ds_read_b128 v[202:205], v188 offset:20480
	ds_read_b128 v[206:209], v188 offset:21504
	ds_read_b128 v[210:213], v188 offset:22528
	ds_read_b128 v[220:223], v188 offset:23552
	s_mov_b32 m0, s54
	s_nop 0
	global_load_lds_dwordx4 v162, s[14:15]
	s_add_i32 m0, s54, 0x2000
	s_nop 0
	global_load_lds_dwordx4 v184, s[14:15]
	s_add_u32 s14, s20, 0x80000
	s_addc_u32 s15, s21, 0
	s_add_i32 s54, s55, s26
	s_mov_b32 m0, s54
	s_nop 0
	global_load_lds_dwordx4 v162, s[14:15]
	s_add_i32 m0, s54, 0x2000
	s_nop 0
	global_load_lds_dwordx4 v184, s[14:15]
	s_mov_b64 s[14:15], s[22:23]
	s_mov_b32 m0, s27
	s_nop 0
	global_load_lds_dwordx4 v1, s[14:15]
	s_mov_b32 m0, s28
	s_nop 0
	global_load_lds_dwordx4 v164, s[14:15]
	s_waitcnt vmcnt(8)
	s_waitcnt lgkmcnt(0)
	s_barrier
; #define PG8_STAGE(bufoff, gbase, voff) do { const char* gb_ = (const char*)(gbase); asm volatile("" : "+s"(gb_)); _Pragma("unroll") for (int _i = 0; _i < 2; ++_i) { unsigned vo_ = (voff)[_i]; asm volatile("" : "+v"(vo_));        \
;         __builtin_amdgcn_global_load_lds((const unsigned*)(gb_ + vo_), (PG8_LAS unsigned*)(lds + (bufoff) + ldsw + _i * 8192), 16, 0, 0); } } while (0)
; #define PG8_LDA(dst, b, h) do { _Pragma("unroll") for (int m = 0; m < 4; ++m) _Pragma("unroll") for (int k = 0; k < 2; ++k) dst[m][k] = *(const PG8_LAS bf16x8*)(lds + PG8_SA(b, h) + aoff + m * 2048 + k * 1024); } while (0)
; #define PG8_LDB(dst, b, h) do { _Pragma("unroll") for (int n = 0; n < 2; ++n) _Pragma("unroll") for (int k = 0; k < 2; ++k) dst[n][k] = *(const PG8_LAS bf16x8*)(lds + PG8_SB(b, h) + boff + n * 2048 + k * 1024); } while (0)
; #define PG8_MMA(ai, bj, At, Bt) do { __builtin_amdgcn_s_setprio(1); _Pragma("unroll") for (int m = 0; m < 4; ++m) _Pragma("unroll") for (int n = 0; n < 2; ++n) _Pragma("unroll") for (int k = 0; k < 2; ++k) \
;         acc[ai][bj][m][n] = __builtin_amdgcn_mfma_f32_16x16x32_bf16(Bt[n][k], At[m][k], acc[ai][bj][m][n], 0, 0, 0); __builtin_amdgcn_s_setprio(0); } while (0)
; #define PG8_WAIT_V(n) asm volatile("s_waitcnt vmcnt(" #n ")" ::: "memory")
; #define PG8_WAIT_L(n) asm volatile("s_waitcnt lgkmcnt(" #n ")" ::: "memory")
; #define PG8_BAR __builtin_amdgcn_s_barrier()
; #define PG8_SCHED __builtin_amdgcn_sched_barrier(0)
; template <class Epi, class Sched, bool ALIGN_EPI = false, bool SP2 = false>
; __device__ __forceinline__ void gemm_phase(PG8_LAS unsigned char* lds, const Gemm g, const Sched& S, const Epi& E) {
;     ...
;             PG8_WAIT_V(8); PG8_WAIT_L(0); PG8_BAR; PG8_MMA(1, 0, At, B0); PG8_MMA(1, 1, At, B1); PG8_BAR; PG8_SCHED;
;             PG8_LDB(B0, 1, 0); PG8_LDB(B1, 1, 1); PG8_SCHED; PG8_LDA(At, 1, 0); PG8_STAGE(PG8_SA(0, 1), a2 + hstep, voffA);
;             PG8_WAIT_V(8); PG8_WAIT_L(0); PG8_BAR; PG8_MMA(0, 0, At, B0); PG8_MMA(0, 1, At, B1); PG8_BAR; PG8_SCHED;
	s_setprio 0
	s_waitcnt lgkmcnt(0)
	v_mfma_f32_16x16x32_bf16 v[62:65], v[82:85], v[178:181], v[62:65]
	v_mfma_f32_16x16x32_bf16 v[62:65], v[86:89], v[190:193], v[62:65]
	v_mfma_f32_16x16x32_bf16 v[46:49], v[82:85], v[194:197], v[46:49]
	v_mfma_f32_16x16x32_bf16 v[46:49], v[86:89], v[198:201], v[46:49]
	v_mfma_f32_16x16x32_bf16 v[30:33], v[82:85], v[202:205], v[30:33]
	v_mfma_f32_16x16x32_bf16 v[30:33], v[86:89], v[206:209], v[30:33]
	v_mfma_f32_16x16x32_bf16 v[14:17], v[82:85], v[210:213], v[14:17]
	v_mfma_f32_16x16x32_bf16 v[14:17], v[86:89], v[220:223], v[14:17]
	v_mfma_f32_16x16x32_bf16 v[58:61], v[90:93], v[178:181], v[58:61]
	v_mfma_f32_16x16x32_bf16 v[58:61], v[94:97], v[190:193], v[58:61]
	v_mfma_f32_16x16x32_bf16 v[42:45], v[90:93], v[194:197], v[42:45]
	v_mfma_f32_16x16x32_bf16 v[42:45], v[94:97], v[198:201], v[42:45]
	v_mfma_f32_16x16x32_bf16 v[26:29], v[90:93], v[202:205], v[26:29]
	v_mfma_f32_16x16x32_bf16 v[26:29], v[94:97], v[206:209], v[26:29]
	v_mfma_f32_16x16x32_bf16 v[10:13], v[90:93], v[210:213], v[10:13]
	v_mfma_f32_16x16x32_bf16 v[10:13], v[94:97], v[220:223], v[10:13]
	v_mfma_f32_16x16x32_bf16 v[54:57], v[146:149], v[178:181], v[54:57]
	v_mfma_f32_16x16x32_bf16 v[54:57], v[150:153], v[190:193], v[54:57]
	v_mfma_f32_16x16x32_bf16 v[38:41], v[146:149], v[194:197], v[38:41]
	v_mfma_f32_16x16x32_bf16 v[38:41], v[150:153], v[198:201], v[38:41]
	v_mfma_f32_16x16x32_bf16 v[22:25], v[146:149], v[202:205], v[22:25]
	v_mfma_f32_16x16x32_bf16 v[22:25], v[150:153], v[206:209], v[22:25]
	v_mfma_f32_16x16x32_bf16 v[6:9], v[146:149], v[210:213], v[6:9]
	v_mfma_f32_16x16x32_bf16 v[6:9], v[150:153], v[220:223], v[6:9]
	v_mfma_f32_16x16x32_bf16 v[50:53], v[154:157], v[178:181], v[50:53]
	v_mfma_f32_16x16x32_bf16 v[50:53], v[158:161], v[190:193], v[50:53]
	v_mfma_f32_16x16x32_bf16 v[34:37], v[154:157], v[194:197], v[34:37]
	v_mfma_f32_16x16x32_bf16 v[34:37], v[158:161], v[198:201], v[34:37]
	v_mfma_f32_16x16x32_bf16 v[18:21], v[154:157], v[202:205], v[18:21]
	v_mfma_f32_16x16x32_bf16 v[18:21], v[158:161], v[206:209], v[18:21]
	v_mfma_f32_16x16x32_bf16 v[2:5], v[154:157], v[210:213], v[2:5]
	v_mfma_f32_16x16x32_bf16 v[2:5], v[158:161], v[220:223], v[2:5]
	s_setprio 1
	s_barrier
	s_add_i32 s54, 0, 0x18000
	s_add_i32 s55, 0, 0x1c000
	ds_read_b128 v[82:85], v244 offset:32768
	ds_read_b128 v[86:89], v244 offset:33792
	ds_read_b128 v[90:93], v244 offset:34816
	ds_read_b128 v[94:97], v244 offset:35840
	ds_read_b128 v[146:149], v244 offset:49152
	ds_read_b128 v[150:153], v244 offset:50176
	ds_read_b128 v[154:157], v244 offset:51200
	ds_read_b128 v[158:161], v244 offset:52224
	s_add_u32 s14, s22, 0x80000
	s_addc_u32 s15, s23, 0
	s_mov_b32 m0, s29
	ds_read_b128 v[178:181], v188 offset:32768
	ds_read_b128 v[190:193], v188 offset:33792
	ds_read_b128 v[194:197], v188 offset:34816
	ds_read_b128 v[198:201], v188 offset:35840
	ds_read_b128 v[202:205], v188 offset:36864
	ds_read_b128 v[206:209], v188 offset:37888
	ds_read_b128 v[210:213], v188 offset:38912
	ds_read_b128 v[220:223], v188 offset:39936
	s_nop 0
	global_load_lds_dwordx4 v1, s[14:15]
	s_mov_b32 m0, s33
	s_nop 0
	global_load_lds_dwordx4 v164, s[14:15]
	s_waitcnt vmcnt(8)
	s_waitcnt lgkmcnt(0)
	s_barrier
	s_setprio 0
	s_waitcnt lgkmcnt(0)
	v_mfma_f32_16x16x32_bf16 v[142:145], v[82:85], v[178:181], v[142:145]
	v_mfma_f32_16x16x32_bf16 v[142:145], v[86:89], v[190:193], v[142:145]
	v_mfma_f32_16x16x32_bf16 v[126:129], v[82:85], v[194:197], v[126:129]
	v_mfma_f32_16x16x32_bf16 v[126:129], v[86:89], v[198:201], v[126:129]
	v_mfma_f32_16x16x32_bf16 v[110:113], v[82:85], v[202:205], v[110:113]
	v_mfma_f32_16x16x32_bf16 v[110:113], v[86:89], v[206:209], v[110:113]
	v_mfma_f32_16x16x32_bf16 v[78:81], v[82:85], v[210:213], v[78:81]
	v_mfma_f32_16x16x32_bf16 v[78:81], v[86:89], v[220:223], v[78:81]
	v_mfma_f32_16x16x32_bf16 v[138:141], v[90:93], v[178:181], v[138:141]
	v_mfma_f32_16x16x32_bf16 v[138:141], v[94:97], v[190:193], v[138:141]
	v_mfma_f32_16x16x32_bf16 v[122:125], v[90:93], v[194:197], v[122:125]
	v_mfma_f32_16x16x32_bf16 v[122:125], v[94:97], v[198:201], v[122:125]
	v_mfma_f32_16x16x32_bf16 v[106:109], v[90:93], v[202:205], v[106:109]
	v_mfma_f32_16x16x32_bf16 v[106:109], v[94:97], v[206:209], v[106:109]
	v_mfma_f32_16x16x32_bf16 v[74:77], v[90:93], v[210:213], v[74:77]
	v_mfma_f32_16x16x32_bf16 v[74:77], v[94:97], v[220:223], v[74:77]
	v_mfma_f32_16x16x32_bf16 v[134:137], v[146:149], v[178:181], v[134:137]
	v_mfma_f32_16x16x32_bf16 v[134:137], v[150:153], v[190:193], v[134:137]
	v_mfma_f32_16x16x32_bf16 v[118:121], v[146:149], v[194:197], v[118:121]
	v_mfma_f32_16x16x32_bf16 v[118:121], v[150:153], v[198:201], v[118:121]
	v_mfma_f32_16x16x32_bf16 v[102:105], v[146:149], v[202:205], v[102:105]
	v_mfma_f32_16x16x32_bf16 v[102:105], v[150:153], v[206:209], v[102:105]
	v_mfma_f32_16x16x32_bf16 v[70:73], v[146:149], v[210:213], v[70:73]
	v_mfma_f32_16x16x32_bf16 v[70:73], v[150:153], v[220:223], v[70:73]
	v_mfma_f32_16x16x32_bf16 v[130:133], v[154:157], v[178:181], v[130:133]
	v_mfma_f32_16x16x32_bf16 v[130:133], v[158:161], v[190:193], v[130:133]
	v_mfma_f32_16x16x32_bf16 v[114:117], v[154:157], v[194:197], v[114:117]
	v_mfma_f32_16x16x32_bf16 v[114:117], v[158:161], v[198:201], v[114:117]
	v_mfma_f32_16x16x32_bf16 v[98:101], v[154:157], v[202:205], v[98:101]
	v_mfma_f32_16x16x32_bf16 v[98:101], v[158:161], v[206:209], v[98:101]
	v_mfma_f32_16x16x32_bf16 v[66:69], v[154:157], v[210:213], v[66:69]
	v_mfma_f32_16x16x32_bf16 v[66:69], v[158:161], v[220:223], v[66:69]
	s_setprio 1
	s_barrier
; #define PG8_STAGE(bufoff, gbase, voff) do { const char* gb_ = (const char*)(gbase); asm volatile("" : "+s"(gb_)); _Pragma("unroll") for (int _i = 0; _i < 2; ++_i) { unsigned vo_ = (voff)[_i]; asm volatile("" : "+v"(vo_));        \
;         __builtin_amdgcn_global_load_lds((const unsigned*)(gb_ + vo_), (PG8_LAS unsigned*)(lds + (bufoff) + ldsw + _i * 8192), 16, 0, 0); } } while (0)
; #define PG8_LDA(dst, b, h) do { _Pragma("unroll") for (int m = 0; m < 4; ++m) _Pragma("unroll") for (int k = 0; k < 2; ++k) dst[m][k] = *(const PG8_LAS bf16x8*)(lds + PG8_SA(b, h) + aoff + m * 2048 + k * 1024); } while (0)
; #define PG8_MMA(ai, bj, At, Bt) do { __builtin_amdgcn_s_setprio(1); _Pragma("unroll") for (int m = 0; m < 4; ++m) _Pragma("unroll") for (int n = 0; n < 2; ++n) _Pragma("unroll") for (int k = 0; k < 2; ++k) \
;         acc[ai][bj][m][n] = __builtin_amdgcn_mfma_f32_16x16x32_bf16(Bt[n][k], At[m][k], acc[ai][bj][m][n], 0, 0, 0); __builtin_amdgcn_s_setprio(0); } while (0)
; #define PG8_WAIT_V(n) asm volatile("s_waitcnt vmcnt(" #n ")" ::: "memory")
; #define PG8_WAIT_L(n) asm volatile("s_waitcnt lgkmcnt(" #n ")" ::: "memory")
; #define PG8_BAR __builtin_amdgcn_s_barrier()
; #define PG8_SCHED __builtin_amdgcn_sched_barrier(0)
; template <class Epi, class Sched, bool ALIGN_EPI = false, bool SP2 = false>
; __device__ __forceinline__ void gemm_phase(PG8_LAS unsigned char* lds, const Gemm g, const Sched& S, const Epi& E) {
;     ...
;             PG8_LDA(At, 1, 1); PG8_STAGE(PG8_SB(1, 0), b3, voffB); PG8_STAGE(PG8_SB(1, 1), b3 + hstep, voffB); PG8_STAGE(PG8_SA(1, 0), a3, voffA);
;             PG8_WAIT_V(8); PG8_WAIT_L(0); PG8_BAR; PG8_MMA(1, 0, At, B0); PG8_MMA(1, 1, At, B1); PG8_BAR; PG8_SCHED;
;     ...
;         if constexpr (ALIGN_EPI) { if (wr == 0) PG8_BAR; }
;         if constexpr (!Epi::AFTER_DRAIN) { E(acc, cur, wr, wc, fr, fq); S.done(cur); }
	s_add_u32 s14, s20, 0x80
	s_addc_u32 s15, s21, 0
	s_add_i32 s22, s54, s26
	ds_read_b128 v[178:181], v188 offset:49152
	ds_read_b128 v[190:193], v188 offset:50176
	ds_read_b128 v[194:197], v188 offset:51200
	ds_read_b128 v[198:201], v188 offset:52224
	ds_read_b128 v[202:205], v188 offset:53248
	ds_read_b128 v[206:209], v188 offset:54272
	ds_read_b128 v[210:213], v188 offset:55296
	ds_read_b128 v[220:223], v188 offset:56320
	s_mov_b32 m0, s22
	s_nop 0
	global_load_lds_dwordx4 v162, s[14:15]
	s_add_i32 m0, s22, 0x2000
	s_nop 0
	global_load_lds_dwordx4 v184, s[14:15]
	s_add_u32 s14, s20, 0x80080
	s_addc_u32 s15, s21, 0
	s_add_i32 s20, s55, s26
	s_mov_b32 m0, s20
	s_nop 0
	global_load_lds_dwordx4 v162, s[14:15]
	s_add_i32 m0, s20, 0x2000
	s_nop 0
	global_load_lds_dwordx4 v184, s[14:15]
	s_mov_b32 m0, s38
	s_nop 0
	global_load_lds_dwordx4 v1, s[18:19]
	s_mov_b32 m0, s39
	s_nop 0
	global_load_lds_dwordx4 v164, s[18:19]
	s_waitcnt vmcnt(8)
	s_waitcnt lgkmcnt(0)
	s_barrier
	s_setprio 0
	s_waitcnt lgkmcnt(0)
	v_mfma_f32_16x16x32_bf16 v[62:65], v[82:85], v[178:181], v[62:65]
	v_mfma_f32_16x16x32_bf16 v[62:65], v[86:89], v[190:193], v[62:65]
	v_mfma_f32_16x16x32_bf16 v[46:49], v[82:85], v[194:197], v[46:49]
	v_mfma_f32_16x16x32_bf16 v[46:49], v[86:89], v[198:201], v[46:49]
	v_mfma_f32_16x16x32_bf16 v[30:33], v[82:85], v[202:205], v[30:33]
	v_mfma_f32_16x16x32_bf16 v[30:33], v[86:89], v[206:209], v[30:33]
	v_mfma_f32_16x16x32_bf16 v[14:17], v[82:85], v[210:213], v[14:17]
	v_mfma_f32_16x16x32_bf16 v[14:17], v[86:89], v[220:223], v[14:17]
	v_mfma_f32_16x16x32_bf16 v[58:61], v[90:93], v[178:181], v[58:61]
	v_mfma_f32_16x16x32_bf16 v[58:61], v[94:97], v[190:193], v[58:61]
	v_mfma_f32_16x16x32_bf16 v[42:45], v[90:93], v[194:197], v[42:45]
	v_mfma_f32_16x16x32_bf16 v[42:45], v[94:97], v[198:201], v[42:45]
	v_mfma_f32_16x16x32_bf16 v[26:29], v[90:93], v[202:205], v[26:29]
	v_mfma_f32_16x16x32_bf16 v[26:29], v[94:97], v[206:209], v[26:29]
	v_mfma_f32_16x16x32_bf16 v[10:13], v[90:93], v[210:213], v[10:13]
	v_mfma_f32_16x16x32_bf16 v[10:13], v[94:97], v[220:223], v[10:13]
	v_mfma_f32_16x16x32_bf16 v[54:57], v[146:149], v[178:181], v[54:57]
	v_mfma_f32_16x16x32_bf16 v[54:57], v[150:153], v[190:193], v[54:57]
	v_mfma_f32_16x16x32_bf16 v[38:41], v[146:149], v[194:197], v[38:41]
	v_mfma_f32_16x16x32_bf16 v[38:41], v[150:153], v[198:201], v[38:41]
	v_mfma_f32_16x16x32_bf16 v[22:25], v[146:149], v[202:205], v[22:25]
	v_mfma_f32_16x16x32_bf16 v[22:25], v[150:153], v[206:209], v[22:25]
	v_mfma_f32_16x16x32_bf16 v[6:9], v[146:149], v[210:213], v[6:9]
	v_mfma_f32_16x16x32_bf16 v[6:9], v[150:153], v[220:223], v[6:9]
	v_mfma_f32_16x16x32_bf16 v[50:53], v[154:157], v[178:181], v[50:53]
	v_mfma_f32_16x16x32_bf16 v[50:53], v[158:161], v[190:193], v[50:53]
	v_mfma_f32_16x16x32_bf16 v[34:37], v[154:157], v[194:197], v[34:37]
	v_mfma_f32_16x16x32_bf16 v[34:37], v[158:161], v[198:201], v[34:37]
	v_mfma_f32_16x16x32_bf16 v[18:21], v[154:157], v[202:205], v[18:21]
	v_mfma_f32_16x16x32_bf16 v[18:21], v[158:161], v[206:209], v[18:21]
	v_mfma_f32_16x16x32_bf16 v[2:5], v[154:157], v[210:213], v[2:5]
	v_mfma_f32_16x16x32_bf16 v[2:5], v[158:161], v[220:223], v[2:5]
	s_setprio 1
	s_barrier
	s_add_i32 s53, s53, 2
	s_add_u32 s51, s51, 0x100
	s_addc_u32 s52, s52, 0
	s_cmp_gt_u32 s53, 29
	s_mov_b64 s[14:15], s[16:17]
	s_cbranch_scc0 .LBB0_634
	s_and_b64 vcc, exec, s[2:3]
	s_cbranch_vccz .LBB0_637
	s_barrier

; #define PG8_STAGE(bufoff, gbase, voff) do { const char* gb_ = (const char*)(gbase); asm volatile("" : "+s"(gb_)); _Pragma("unroll") for (int _i = 0; _i < 2; ++_i) { unsigned vo_ = (voff)[_i]; asm volatile("" : "+v"(vo_));        \
;         __builtin_amdgcn_global_load_lds((const unsigned*)(gb_ + vo_), (PG8_LAS unsigned*)(lds + (bufoff) + ldsw + _i * 8192), 16, 0, 0); } } while (0)
; #define PG8_LDA(dst, b, h) do { _Pragma("unroll") for (int m = 0; m < 4; ++m) _Pragma("unroll") for (int k = 0; k < 2; ++k) dst[m][k] = *(const PG8_LAS bf16x8*)(lds + PG8_SA(b, h) + aoff + m * 2048 + k * 1024); } while (0)
; #define PG8_LDB(dst, b, h) do { _Pragma("unroll") for (int n = 0; n < 2; ++n) _Pragma("unroll") for (int k = 0; k < 2; ++k) dst[n][k] = *(const PG8_LAS bf16x8*)(lds + PG8_SB(b, h) + boff + n * 2048 + k * 1024); } while (0)
; #define PG8_MMA(ai, bj, At, Bt) do { __builtin_amdgcn_s_setprio(1); _Pragma("unroll") for (int m = 0; m < 4; ++m) _Pragma("unroll") for (int n = 0; n < 2; ++n) _Pragma("unroll") for (int k = 0; k < 2; ++k) \
;         acc[ai][bj][m][n] = __builtin_amdgcn_mfma_f32_16x16x32_bf16(Bt[n][k], At[m][k], acc[ai][bj][m][n], 0, 0, 0); __builtin_amdgcn_s_setprio(0); } while (0)
; #define PG8_WAIT_V(n) asm volatile("s_waitcnt vmcnt(" #n ")" ::: "memory")
; #define PG8_BAR __builtin_amdgcn_s_barrier()
; template <class Epi, class Sched, bool ALIGN_EPI = false, bool SP2 = false>
; __device__ __forceinline__ void gemm_phase(PG8_LAS unsigned char* lds, const Gemm g, const Sched& S, const Epi& E) {
;     ...
;             const char* a1 = cA + (size_t)(t + 1) * kstep;
;             const char* a2 = last ? nA : cA + (size_t)(t + 2) * kstep; const char* b2 = last ? nB : cB + (size_t)(t + 2) * kstep;
;             const char* a3 = a2 + kstep; const char* b3 = b2 + kstep;
;             if (last && has_next) S.a_ready(nxt);
;             if constexpr (SP2) {
;             PG8_LDB(B0, 0, 0); PG8_LDB(B1, 0, 1); PG8_SCHED; PG8_LDA(At, 0, 0); PG8_STAGE(PG8_SA(1, 1), a1 + hstep, voffA);
;             PG8_WAIT_V(8); PG8_WAIT_L(0); PG8_BAR; PG8_MMA(0, 0, At, B0); PG8_MMA(0, 1, At, B1); PG8_BAR; PG8_SCHED;
;             PG8_LDA(At, 0, 1); PG8_STAGE(PG8_SB(0, 0), b2, voffB); PG8_STAGE(PG8_SB(0, 1), b2 + hstep, voffB); PG8_STAGE(PG8_SA(0, 0), a2, voffA);
;             PG8_WAIT_V(8); PG8_WAIT_L(0); PG8_BAR; PG8_MMA(1, 0, At, B0); PG8_MMA(1, 1, At, B1); PG8_BAR; PG8_SCHED;
.LBB0_707:
	s_add_u32 s2, s4, 0x100
	s_addc_u32 s3, s5, 0
	s_cmpk_eq_i32 s35, 0x54
	s_cselect_b32 s10, s52, s2
	s_cselect_b32 s11, s53, s3
	s_cselect_b32 s8, s42, s31
	s_cselect_b32 s9, s43, s34
	s_add_u32 s6, s10, 0x80
	s_addc_u32 s7, s11, 0
	s_add_i32 s38, 0, 0x10000
	s_add_i32 s39, 0, 0x14000
	ds_read_b128 v[34:37], v244
	ds_read_b128 v[38:41], v244 offset:1024
	ds_read_b128 v[98:101], v244 offset:2048
	ds_read_b128 v[102:105], v244 offset:3072
	ds_read_b128 v[146:149], v244 offset:16384
	ds_read_b128 v[150:153], v244 offset:17408
	ds_read_b128 v[154:157], v244 offset:18432
	ds_read_b128 v[158:161], v244 offset:19456
	s_add_u32 s4, s4, 0x160080
	s_addc_u32 s5, s5, 0
	ds_read_b128 v[178:181], v194
	ds_read_b128 v[182:185], v194 offset:1024
	ds_read_b128 v[186:189], v194 offset:2048
	ds_read_b128 v[196:199], v194 offset:3072
	ds_read_b128 v[200:203], v194 offset:4096
	ds_read_b128 v[204:207], v194 offset:5120
	ds_read_b128 v[208:211], v194 offset:6144
	ds_read_b128 v[212:215], v194 offset:7168
	s_add_i32 m0, s16, 0xc000
	s_nop 0
	global_load_lds_dwordx4 v1, s[4:5]
	s_add_i32 m0, s16, 0xe000
	s_nop 0
	global_load_lds_dwordx4 v164, s[4:5]
	s_waitcnt vmcnt(8)
	s_waitcnt lgkmcnt(0)
	s_barrier
	s_setprio 0
	s_waitcnt lgkmcnt(0)
	v_mfma_f32_16x16x32_bf16 v[142:145], v[34:37], v[178:181], v[142:145]
	v_mfma_f32_16x16x32_bf16 v[142:145], v[38:41], v[182:185], v[142:145]
	v_mfma_f32_16x16x32_bf16 v[134:137], v[34:37], v[186:189], v[134:137]
	v_mfma_f32_16x16x32_bf16 v[134:137], v[38:41], v[196:199], v[134:137]
	v_mfma_f32_16x16x32_bf16 v[126:129], v[34:37], v[200:203], v[126:129]
	v_mfma_f32_16x16x32_bf16 v[126:129], v[38:41], v[204:207], v[126:129]
	v_mfma_f32_16x16x32_bf16 v[118:121], v[34:37], v[208:211], v[118:121]
	v_mfma_f32_16x16x32_bf16 v[118:121], v[38:41], v[212:215], v[118:121]
	v_mfma_f32_16x16x32_bf16 v[138:141], v[98:101], v[178:181], v[138:141]
	v_mfma_f32_16x16x32_bf16 v[138:141], v[102:105], v[182:185], v[138:141]
	v_mfma_f32_16x16x32_bf16 v[130:133], v[98:101], v[186:189], v[130:133]
	v_mfma_f32_16x16x32_bf16 v[130:133], v[102:105], v[196:199], v[130:133]
	v_mfma_f32_16x16x32_bf16 v[122:125], v[98:101], v[200:203], v[122:125]
	v_mfma_f32_16x16x32_bf16 v[122:125], v[102:105], v[204:207], v[122:125]
	v_mfma_f32_16x16x32_bf16 v[114:117], v[98:101], v[208:211], v[114:117]
	v_mfma_f32_16x16x32_bf16 v[114:117], v[102:105], v[212:215], v[114:117]
	v_mfma_f32_16x16x32_bf16 v[70:73], v[146:149], v[178:181], v[70:73]
	v_mfma_f32_16x16x32_bf16 v[70:73], v[150:153], v[182:185], v[70:73]
	v_mfma_f32_16x16x32_bf16 v[62:65], v[146:149], v[186:189], v[62:65]
	v_mfma_f32_16x16x32_bf16 v[62:65], v[150:153], v[196:199], v[62:65]
	v_mfma_f32_16x16x32_bf16 v[54:57], v[146:149], v[200:203], v[54:57]
	v_mfma_f32_16x16x32_bf16 v[54:57], v[150:153], v[204:207], v[54:57]
	v_mfma_f32_16x16x32_bf16 v[46:49], v[146:149], v[208:211], v[46:49]
	v_mfma_f32_16x16x32_bf16 v[46:49], v[150:153], v[212:215], v[46:49]
	v_mfma_f32_16x16x32_bf16 v[66:69], v[154:157], v[178:181], v[66:69]
	v_mfma_f32_16x16x32_bf16 v[66:69], v[158:161], v[182:185], v[66:69]
	v_mfma_f32_16x16x32_bf16 v[58:61], v[154:157], v[186:189], v[58:61]
	v_mfma_f32_16x16x32_bf16 v[58:61], v[158:161], v[196:199], v[58:61]
	v_mfma_f32_16x16x32_bf16 v[50:53], v[154:157], v[200:203], v[50:53]
	v_mfma_f32_16x16x32_bf16 v[50:53], v[158:161], v[204:207], v[50:53]
	v_mfma_f32_16x16x32_bf16 v[42:45], v[154:157], v[208:211], v[42:45]
	v_mfma_f32_16x16x32_bf16 v[42:45], v[158:161], v[212:215], v[42:45]
	s_setprio 1
	s_barrier
	s_mov_b64 s[4:5], s[8:9]
	s_add_i32 s38, s38, s15
	ds_read_b128 v[178:181], v194 offset:16384
	ds_read_b128 v[182:185], v194 offset:17408
	ds_read_b128 v[186:189], v194 offset:18432
	ds_read_b128 v[196:199], v194 offset:19456
	ds_read_b128 v[200:203], v194 offset:20480
	ds_read_b128 v[204:207], v194 offset:21504
	ds_read_b128 v[208:211], v194 offset:22528
	ds_read_b128 v[212:215], v194 offset:23552
	s_mov_b32 m0, s38
	s_nop 0
	global_load_lds_dwordx4 v162, s[4:5]
	s_add_i32 m0, s38, 0x2000
	s_nop 0
	global_load_lds_dwordx4 v190, s[4:5]
	s_add_u32 s4, s8, 0x160000
	s_addc_u32 s5, s9, 0
	s_add_i32 s38, s39, s15
	s_mov_b32 m0, s38
	s_nop 0
	global_load_lds_dwordx4 v162, s[4:5]
	s_add_i32 m0, s38, 0x2000
	s_nop 0
	global_load_lds_dwordx4 v190, s[4:5]
	s_mov_b64 s[4:5], s[10:11]
	s_mov_b32 m0, s16
	s_nop 0
	global_load_lds_dwordx4 v1, s[4:5]
	s_mov_b32 m0, s17
	s_nop 0
	global_load_lds_dwordx4 v164, s[4:5]
	s_waitcnt vmcnt(8)
	s_waitcnt lgkmcnt(0)
	s_barrier
	s_setprio 0
	s_waitcnt lgkmcnt(0)
	v_mfma_f32_16x16x32_bf16 v[110:113], v[34:37], v[178:181], v[110:113]
	v_mfma_f32_16x16x32_bf16 v[110:113], v[38:41], v[182:185], v[110:113]
	v_mfma_f32_16x16x32_bf16 v[94:97], v[34:37], v[186:189], v[94:97]
	v_mfma_f32_16x16x32_bf16 v[94:97], v[38:41], v[196:199], v[94:97]
	v_mfma_f32_16x16x32_bf16 v[86:89], v[34:37], v[200:203], v[86:89]
	v_mfma_f32_16x16x32_bf16 v[86:89], v[38:41], v[204:207], v[86:89]
	v_mfma_f32_16x16x32_bf16 v[34:37], v[34:37], v[208:211], v[78:81]
	v_mfma_f32_16x16x32_bf16 v[34:37], v[38:41], v[212:215], v[34:37]
	v_mfma_f32_16x16x32_bf16 v[106:109], v[98:101], v[178:181], v[106:109]
	v_mfma_f32_16x16x32_bf16 v[106:109], v[102:105], v[182:185], v[106:109]
	v_mfma_f32_16x16x32_bf16 v[90:93], v[98:101], v[186:189], v[90:93]
	v_mfma_f32_16x16x32_bf16 v[90:93], v[102:105], v[196:199], v[90:93]
	v_mfma_f32_16x16x32_bf16 v[82:85], v[98:101], v[200:203], v[82:85]
	v_mfma_f32_16x16x32_bf16 v[82:85], v[102:105], v[204:207], v[82:85]
	v_mfma_f32_16x16x32_bf16 v[38:41], v[98:101], v[208:211], v[74:77]
	v_mfma_f32_16x16x32_bf16 v[38:41], v[102:105], v[212:215], v[38:41]
	v_mfma_f32_16x16x32_bf16 v[30:33], v[146:149], v[178:181], v[30:33]
	v_mfma_f32_16x16x32_bf16 v[30:33], v[150:153], v[182:185], v[30:33]
	v_mfma_f32_16x16x32_bf16 v[22:25], v[146:149], v[186:189], v[22:25]
	v_mfma_f32_16x16x32_bf16 v[22:25], v[150:153], v[196:199], v[22:25]
	v_mfma_f32_16x16x32_bf16 v[14:17], v[146:149], v[200:203], v[14:17]
	v_mfma_f32_16x16x32_bf16 v[14:17], v[150:153], v[204:207], v[14:17]
	v_mfma_f32_16x16x32_bf16 v[6:9], v[146:149], v[208:211], v[6:9]
	v_mfma_f32_16x16x32_bf16 v[6:9], v[150:153], v[212:215], v[6:9]
	v_mfma_f32_16x16x32_bf16 v[26:29], v[154:157], v[178:181], v[26:29]
	v_mfma_f32_16x16x32_bf16 v[26:29], v[158:161], v[182:185], v[26:29]
	v_mfma_f32_16x16x32_bf16 v[18:21], v[154:157], v[186:189], v[18:21]
	v_mfma_f32_16x16x32_bf16 v[18:21], v[158:161], v[196:199], v[18:21]
	v_mfma_f32_16x16x32_bf16 v[10:13], v[154:157], v[200:203], v[10:13]
	v_mfma_f32_16x16x32_bf16 v[10:13], v[158:161], v[204:207], v[10:13]
	v_mfma_f32_16x16x32_bf16 v[2:5], v[154:157], v[208:211], v[2:5]
	v_mfma_f32_16x16x32_bf16 v[2:5], v[158:161], v[212:215], v[2:5]
	s_setprio 1
	s_barrier
; #define PG8_STAGE(bufoff, gbase, voff) do { const char* gb_ = (const char*)(gbase); asm volatile("" : "+s"(gb_)); _Pragma("unroll") for (int _i = 0; _i < 2; ++_i) { unsigned vo_ = (voff)[_i]; asm volatile("" : "+v"(vo_));        \
;         __builtin_amdgcn_global_load_lds((const unsigned*)(gb_ + vo_), (PG8_LAS unsigned*)(lds + (bufoff) + ldsw + _i * 8192), 16, 0, 0); } } while (0)
; #define PG8_LDA(dst, b, h) do { _Pragma("unroll") for (int m = 0; m < 4; ++m) _Pragma("unroll") for (int k = 0; k < 2; ++k) dst[m][k] = *(const PG8_LAS bf16x8*)(lds + PG8_SA(b, h) + aoff + m * 2048 + k * 1024); } while (0)
; #define PG8_LDB(dst, b, h) do { _Pragma("unroll") for (int n = 0; n < 2; ++n) _Pragma("unroll") for (int k = 0; k < 2; ++k) dst[n][k] = *(const PG8_LAS bf16x8*)(lds + PG8_SB(b, h) + boff + n * 2048 + k * 1024); } while (0)
; #define PG8_MMA(ai, bj, At, Bt) do { __builtin_amdgcn_s_setprio(1); _Pragma("unroll") for (int m = 0; m < 4; ++m) _Pragma("unroll") for (int n = 0; n < 2; ++n) _Pragma("unroll") for (int k = 0; k < 2; ++k) \
;         acc[ai][bj][m][n] = __builtin_amdgcn_mfma_f32_16x16x32_bf16(Bt[n][k], At[m][k], acc[ai][bj][m][n], 0, 0, 0); __builtin_amdgcn_s_setprio(0); } while (0)
; #define PG8_WAIT_V(n) asm volatile("s_waitcnt vmcnt(" #n ")" ::: "memory")
; #define PG8_WAIT_L(n) asm volatile("s_waitcnt lgkmcnt(" #n ")" ::: "memory")
; #define PG8_BAR __builtin_amdgcn_s_barrier()
; #define PG8_SCHED __builtin_amdgcn_sched_barrier(0)
; template <class Epi, class Sched, bool ALIGN_EPI = false, bool SP2 = false>
; __device__ __forceinline__ void gemm_phase(PG8_LAS unsigned char* lds, const Gemm g, const Sched& S, const Epi& E) {
;     ...
;             PG8_LDB(B0, 1, 0); PG8_LDB(B1, 1, 1); PG8_SCHED; PG8_LDA(At, 1, 0); PG8_STAGE(PG8_SA(0, 1), a2 + hstep, voffA);
;             PG8_WAIT_V(8); PG8_WAIT_L(0); PG8_BAR; PG8_MMA(0, 0, At, B0); PG8_MMA(0, 1, At, B1); PG8_BAR; PG8_SCHED;
;             PG8_LDA(At, 1, 1); PG8_STAGE(PG8_SB(1, 0), b3, voffB); PG8_STAGE(PG8_SB(1, 1), b3 + hstep, voffB); PG8_STAGE(PG8_SA(1, 0), a3, voffA);
;             PG8_WAIT_V(8); PG8_WAIT_L(0); PG8_BAR; PG8_MMA(1, 0, At, B0); PG8_MMA(1, 1, At, B1); PG8_BAR; PG8_SCHED;
	s_add_i32 s38, 0, 0x18000
	s_add_i32 s39, 0, 0x1c000
	ds_read_b128 v[74:77], v244 offset:32768
	ds_read_b128 v[78:81], v244 offset:33792
	ds_read_b128 v[98:101], v244 offset:34816
	ds_read_b128 v[102:105], v244 offset:35840
	ds_read_b128 v[146:149], v244 offset:49152
	ds_read_b128 v[150:153], v244 offset:50176
	ds_read_b128 v[154:157], v244 offset:51200
	ds_read_b128 v[158:161], v244 offset:52224
	s_add_u32 s4, s10, 0x160000
	s_addc_u32 s5, s11, 0
	s_mov_b32 m0, s18
	ds_read_b128 v[178:181], v194 offset:32768
	ds_read_b128 v[182:185], v194 offset:33792
	ds_read_b128 v[186:189], v194 offset:34816
	ds_read_b128 v[196:199], v194 offset:35840
	ds_read_b128 v[200:203], v194 offset:36864
	ds_read_b128 v[204:207], v194 offset:37888
	ds_read_b128 v[208:211], v194 offset:38912
	ds_read_b128 v[212:215], v194 offset:39936
	s_nop 0
	global_load_lds_dwordx4 v1, s[4:5]
	s_mov_b32 m0, s19
	s_nop 0
	global_load_lds_dwordx4 v164, s[4:5]
	s_waitcnt vmcnt(8)
	s_waitcnt lgkmcnt(0)
	s_barrier
	s_setprio 0
	s_waitcnt lgkmcnt(0)
	v_mfma_f32_16x16x32_bf16 v[142:145], v[74:77], v[178:181], v[142:145]
	v_mfma_f32_16x16x32_bf16 v[142:145], v[78:81], v[182:185], v[142:145]
	v_mfma_f32_16x16x32_bf16 v[134:137], v[74:77], v[186:189], v[134:137]
	v_mfma_f32_16x16x32_bf16 v[134:137], v[78:81], v[196:199], v[134:137]
	v_mfma_f32_16x16x32_bf16 v[126:129], v[74:77], v[200:203], v[126:129]
	v_mfma_f32_16x16x32_bf16 v[126:129], v[78:81], v[204:207], v[126:129]
	v_mfma_f32_16x16x32_bf16 v[118:121], v[74:77], v[208:211], v[118:121]
	v_mfma_f32_16x16x32_bf16 v[118:121], v[78:81], v[212:215], v[118:121]
	v_mfma_f32_16x16x32_bf16 v[138:141], v[98:101], v[178:181], v[138:141]
	v_mfma_f32_16x16x32_bf16 v[138:141], v[102:105], v[182:185], v[138:141]
	v_mfma_f32_16x16x32_bf16 v[130:133], v[98:101], v[186:189], v[130:133]
	v_mfma_f32_16x16x32_bf16 v[130:133], v[102:105], v[196:199], v[130:133]
	v_mfma_f32_16x16x32_bf16 v[122:125], v[98:101], v[200:203], v[122:125]
	v_mfma_f32_16x16x32_bf16 v[122:125], v[102:105], v[204:207], v[122:125]
	v_mfma_f32_16x16x32_bf16 v[114:117], v[98:101], v[208:211], v[114:117]
	v_mfma_f32_16x16x32_bf16 v[114:117], v[102:105], v[212:215], v[114:117]
	v_mfma_f32_16x16x32_bf16 v[70:73], v[146:149], v[178:181], v[70:73]
	v_mfma_f32_16x16x32_bf16 v[70:73], v[150:153], v[182:185], v[70:73]
	v_mfma_f32_16x16x32_bf16 v[62:65], v[146:149], v[186:189], v[62:65]
	v_mfma_f32_16x16x32_bf16 v[62:65], v[150:153], v[196:199], v[62:65]
	v_mfma_f32_16x16x32_bf16 v[54:57], v[146:149], v[200:203], v[54:57]
	v_mfma_f32_16x16x32_bf16 v[54:57], v[150:153], v[204:207], v[54:57]
	v_mfma_f32_16x16x32_bf16 v[46:49], v[146:149], v[208:211], v[46:49]
	v_mfma_f32_16x16x32_bf16 v[46:49], v[150:153], v[212:215], v[46:49]
	v_mfma_f32_16x16x32_bf16 v[66:69], v[154:157], v[178:181], v[66:69]
	v_mfma_f32_16x16x32_bf16 v[66:69], v[158:161], v[182:185], v[66:69]
	v_mfma_f32_16x16x32_bf16 v[58:61], v[154:157], v[186:189], v[58:61]
	v_mfma_f32_16x16x32_bf16 v[58:61], v[158:161], v[196:199], v[58:61]
	v_mfma_f32_16x16x32_bf16 v[50:53], v[154:157], v[200:203], v[50:53]
	v_mfma_f32_16x16x32_bf16 v[50:53], v[158:161], v[204:207], v[50:53]
	v_mfma_f32_16x16x32_bf16 v[42:45], v[154:157], v[208:211], v[42:45]
	v_mfma_f32_16x16x32_bf16 v[42:45], v[158:161], v[212:215], v[42:45]
	s_setprio 1
	s_barrier
	s_add_u32 s4, s8, 0x80
	s_addc_u32 s5, s9, 0
	s_add_i32 s10, s38, s15
	ds_read_b128 v[178:181], v194 offset:49152
	ds_read_b128 v[182:185], v194 offset:50176
	ds_read_b128 v[186:189], v194 offset:51200
	ds_read_b128 v[196:199], v194 offset:52224
	ds_read_b128 v[200:203], v194 offset:53248
	ds_read_b128 v[204:207], v194 offset:54272
	ds_read_b128 v[208:211], v194 offset:55296
	ds_read_b128 v[212:215], v194 offset:56320
	s_mov_b32 m0, s10
	s_nop 0
	global_load_lds_dwordx4 v162, s[4:5]
	s_add_i32 m0, s10, 0x2000
	s_nop 0
	global_load_lds_dwordx4 v190, s[4:5]
	s_add_u32 s4, s8, 0x160080
	s_addc_u32 s5, s9, 0
	s_add_i32 s8, s39, s15
	s_mov_b32 m0, s8
	s_nop 0
	global_load_lds_dwordx4 v162, s[4:5]
	s_add_i32 m0, s8, 0x2000
	s_nop 0
	global_load_lds_dwordx4 v190, s[4:5]
	s_mov_b32 m0, s24
	s_nop 0
	global_load_lds_dwordx4 v1, s[6:7]
	s_mov_b32 m0, s25
	s_nop 0
	global_load_lds_dwordx4 v164, s[6:7]
	s_waitcnt vmcnt(8)
	s_waitcnt lgkmcnt(0)
	s_barrier
; #define PG8_MMA(ai, bj, At, Bt) do { __builtin_amdgcn_s_setprio(1); _Pragma("unroll") for (int m = 0; m < 4; ++m) _Pragma("unroll") for (int n = 0; n < 2; ++n) _Pragma("unroll") for (int k = 0; k < 2; ++k) \
;         acc[ai][bj][m][n] = __builtin_amdgcn_mfma_f32_16x16x32_bf16(Bt[n][k], At[m][k], acc[ai][bj][m][n], 0, 0, 0); __builtin_amdgcn_s_setprio(0); } while (0)
; #define PG8_WAIT_V(n) asm volatile("s_waitcnt vmcnt(" #n ")" ::: "memory")
; #define PG8_WAIT_L(n) asm volatile("s_waitcnt lgkmcnt(" #n ")" ::: "memory")
; #define PG8_BAR __builtin_amdgcn_s_barrier()
; #define PG8_SCHED __builtin_amdgcn_sched_barrier(0)
;     __device__ __forceinline__ void operator()(const f32x4 (&acc)[2][2][4][2], const Unit& u, int wr, int wc, int fr, int fq) const {
;         const int row0 = u.pm * BM + wr * 64 + fr, col0 = u.pn * BM + wc * 32 + 8 * fq, b = (u.pm * BM) / rows_per_batch;
;         const float* g = gate + (size_t)b * gate_bstride + col0;
;         float ssq[2][4];
; #pragma unroll
;         for (int ai = 0; ai < 2; ++ai)
; #pragma unroll
;             for (int m = 0; m < 4; ++m) ssq[ai][m] = 0.f;
;         f32x4 gv[2][2], Gv[2][2];
; #pragma unroll
;         for (int bj = 0; bj < 2; ++bj) { gv[bj][0] = *(const f32x4*)(g + bj * HALF); gv[bj][1] = *(const f32x4*)(g + bj * HALF + 4); Gv[bj][0] = (f32x4){0.f, 0.f, 0.f, 0.f}; Gv[bj][1] = (f32x4){0.f, 0.f, 0.f, 0.f};
;             if (Hn) { const float* sc = scnext + (size_t)b * gate_bstride + col0 + bj * HALF;
;                 Gv[bj][0] = *(const f32x4*)(gnext + col0 + bj * HALF) * (1.0f + *(const f32x4*)(sc)); Gv[bj][1] = *(const f32x4*)(gnext + col0 + bj * HALF + 4) * (1.0f + *(const f32x4*)(sc + 4)); } }
; template <class Epi, class Sched, bool ALIGN_EPI = false, bool SP2 = false>
; __device__ __forceinline__ void gemm_phase(PG8_LAS unsigned char* lds, const Gemm g, const Sched& S, const Epi& E) {
;     ...
;             PG8_WAIT_V(8); PG8_WAIT_L(0); PG8_BAR; PG8_MMA(1, 0, At, B0); PG8_MMA(1, 1, At, B1); PG8_BAR; PG8_SCHED;
	s_setprio 0
	s_waitcnt lgkmcnt(0)
	v_mfma_f32_16x16x32_bf16 v[110:113], v[74:77], v[178:181], v[110:113]
	v_mfma_f32_16x16x32_bf16 v[110:113], v[78:81], v[182:185], v[110:113]
	v_mfma_f32_16x16x32_bf16 v[94:97], v[74:77], v[186:189], v[94:97]
	v_mfma_f32_16x16x32_bf16 v[94:97], v[78:81], v[196:199], v[94:97]
	v_mfma_f32_16x16x32_bf16 v[86:89], v[74:77], v[200:203], v[86:89]
	v_mfma_f32_16x16x32_bf16 v[86:89], v[78:81], v[204:207], v[86:89]
	v_mfma_f32_16x16x32_bf16 v[34:37], v[74:77], v[208:211], v[34:37]
	v_mfma_f32_16x16x32_bf16 v[78:81], v[78:81], v[212:215], v[34:37]
	v_mfma_f32_16x16x32_bf16 v[106:109], v[98:101], v[178:181], v[106:109]
	v_mfma_f32_16x16x32_bf16 v[106:109], v[102:105], v[182:185], v[106:109]
	v_mfma_f32_16x16x32_bf16 v[90:93], v[98:101], v[186:189], v[90:93]
	v_mfma_f32_16x16x32_bf16 v[90:93], v[102:105], v[196:199], v[90:93]
	v_mfma_f32_16x16x32_bf16 v[82:85], v[98:101], v[200:203], v[82:85]
	v_mfma_f32_16x16x32_bf16 v[82:85], v[102:105], v[204:207], v[82:85]
	v_mfma_f32_16x16x32_bf16 v[34:37], v[98:101], v[208:211], v[38:41]
	v_mfma_f32_16x16x32_bf16 v[74:77], v[102:105], v[212:215], v[34:37]
	v_mfma_f32_16x16x32_bf16 v[30:33], v[146:149], v[178:181], v[30:33]
	v_mfma_f32_16x16x32_bf16 v[30:33], v[150:153], v[182:185], v[30:33]
	v_mfma_f32_16x16x32_bf16 v[22:25], v[146:149], v[186:189], v[22:25]
	v_mfma_f32_16x16x32_bf16 v[22:25], v[150:153], v[196:199], v[22:25]
	v_mfma_f32_16x16x32_bf16 v[14:17], v[146:149], v[200:203], v[14:17]
	v_mfma_f32_16x16x32_bf16 v[14:17], v[150:153], v[204:207], v[14:17]
	v_mfma_f32_16x16x32_bf16 v[6:9], v[146:149], v[208:211], v[6:9]
	v_mfma_f32_16x16x32_bf16 v[6:9], v[150:153], v[212:215], v[6:9]
	v_mfma_f32_16x16x32_bf16 v[26:29], v[154:157], v[178:181], v[26:29]
	v_mfma_f32_16x16x32_bf16 v[26:29], v[158:161], v[182:185], v[26:29]
	v_mfma_f32_16x16x32_bf16 v[18:21], v[154:157], v[186:189], v[18:21]
	v_mfma_f32_16x16x32_bf16 v[18:21], v[158:161], v[196:199], v[18:21]
	v_mfma_f32_16x16x32_bf16 v[10:13], v[154:157], v[200:203], v[10:13]
	v_mfma_f32_16x16x32_bf16 v[10:13], v[158:161], v[204:207], v[10:13]
	v_mfma_f32_16x16x32_bf16 v[2:5], v[154:157], v[208:211], v[2:5]
	v_mfma_f32_16x16x32_bf16 v[2:5], v[158:161], v[212:215], v[2:5]
	s_setprio 1
	s_barrier
	s_add_i32 s35, s35, 2
	s_add_u32 s31, s31, 0x100
	s_addc_u32 s34, s34, 0
	s_cmpk_gt_u32 s35, 0x55
	s_mov_b64 s[4:5], s[2:3]
	s_cbranch_scc0 .LBB0_707
	s_ashr_i32 s2, s29, 31
	s_lshr_b32 s2, s2, 27
	s_add_i32 s2, s29, s2
	s_ashr_i32 s2, s2, 5
	v_lshl_or_b32 v156, s30, 8, v193
	s_mul_i32 s5, s2, 0xc000
	v_ashrrev_i32_e32 v157, 31, v156
	s_mul_hi_i32 s4, s2, 0xc000
	s_add_u32 s2, s20, s5
	s_addc_u32 s3, s21, s4
	v_lshlrev_b64 v[34:35], 2, v[156:157]
	v_lshl_add_u64 v[38:39], s[2:3], 0, v[34:35]
	global_load_dwordx4 v[98:101], v[38:39], off offset:16
	global_load_dwordx4 v[102:105], v[38:39], off
	s_add_u32 s2, s22, s5
	s_addc_u32 s3, s23, s4
	v_lshl_add_u64 v[148:149], s[2:3], 0, v[34:35]
	v_lshl_add_u64 v[146:147], s[48:49], 0, v[34:35]
	v_mov_b32_e32 v158, 0
	v_cndmask_b32_e64 v34, 0, 1, s[46:47]
	v_cmp_ne_u32_e64 s[2:3], 1, v34
	s_andn2_b64 vcc, exec, s[46:47]
	v_mov_b32_e32 v159, v158
	v_mov_b32_e32 v160, v158
	v_mov_b32_e32 v161, v158
	v_mov_b32_e32 v178, v158
	v_mov_b32_e32 v179, v158
	v_mov_b32_e32 v180, v158
	v_mov_b32_e32 v181, v158
	s_cbranch_vccnz .LBB0_710
	global_load_dwordx4 v[34:37], v[148:149], off
	global_load_dwordx4 v[150:153], v[148:149], off offset:16
	global_load_dwordx4 v[158:161], v[146:147], off
	global_load_dwordx4 v[178:181], v[146:147], off offset:16
	s_waitcnt vmcnt(0)
	v_pk_add_f32 v[36:37], v[36:37], 1.0 op_sel_hi:[1,0]
	v_pk_add_f32 v[34:35], v[34:35], 1.0 op_sel_hi:[1,0]
	v_pk_add_f32 v[40:41], v[152:153], 1.0 op_sel_hi:[1,0]
	v_pk_add_f32 v[150:151], v[150:151], 1.0 op_sel_hi:[1,0]
	v_pk_mul_f32 v[160:161], v[160:161], v[36:37]
	v_pk_mul_f32 v[158:159], v[158:159], v[34:35]
	v_pk_mul_f32 v[180:181], v[180:181], v[40:41]
	v_pk_mul_f32 v[178:179], v[178:179], v[150:151]
